# mixer pass 1: remaining flat stores/loads (ret_m1, hg_m1 state stores etc.) converted to global
# baseline (speedup 1.0000x reference)
; #define LAS __attribute__((address_space(3)))
; __device__ __forceinline__ void ld8bf(const bf16_t* p, float (&o)[8]) { unpack8(*(const u32x4*)p, o); }
; __device__ __forceinline__ float ret_lg(int h) { return log1pf(-exp2f(-5.0f - (float)h)); }
; __device__ __forceinline__ void w_ret_m1(unsigned char* ws, const bf16_t* proj, LAS unsigned char* wl, int b, int ck_, int h, int lane) {
;     LAS bf16_t* vT = (LAS bf16_t*)wl; LAS bf16_t* kT = (LAS bf16_t*)(wl + TILE_B);
;     const int row0 = b * SEQ + 64 * ck_, lo = lane & 15, fq = lane >> 4; const float lg = ret_lg(h);
;     const float* cosT = (const float*)(ws + WS_ROPE); const float* sinT = cosT + SEQ * 32;
; #pragma unroll
;     for (int i = 0; i < 4; ++i) { const int m = (lane >> 2) + 16 * i, cp = lane & 3; float x1[8], x2[8];
;         const bf16_t* src = proj + (size_t)(row0 + m) * NIN + C_RK + 64 * h; ld8bf(src + 8 * cp, x1); ld8bf(src + 32 + 8 * cp, x2);
;         const float* cp_ = cosT + (64 * ck_ + m) * 32 + 8 * cp; const float* sp_ = sinT + (64 * ck_ + m) * 32 + 8 * cp;
;         const float sc = 0.125f * __expf((float)(63 - m) * lg);
.LBB0_516:
	s_lshr_b32 s21, s20, 8
	s_lshr_b32 s24, s20, 9
	s_add_i32 s21, s21, s20
	s_and_b32 s24, s24, 12
	s_add_i32 s21, s21, s24
	s_and_b32 s24, s21, 12
	s_cmp_lg_u32 s24, 8
	s_cbranch_scc1 .LBB0_515
	s_and_b32 s34, s21, 11
	s_ashr_i32 s21, s20, 31
	s_ashr_i32 s24, s20, 4
	s_lshr_b32 s21, s21, 25
	s_add_i32 s34, s34, -8
	s_add_i32 s27, s24, s21
	v_cvt_f32_u32_e32 v0, s34
	s_ashr_i32 s21, s27, 7
	s_and_b32 s27, s27, 0xffffff80
	s_sub_i32 s27, s24, s27
	s_lshl_b32 s24, s21, 13
	s_lshl_b32 s38, s27, 6
	s_add_i32 s35, s38, s24
	v_sub_f32_e32 v0, 0xc0a00000, v0
	s_mov_b32 s24, 0xc2fc0000
	v_cmp_gt_f32_e32 vcc, s24, v0
	s_and_b64 s[40:41], vcc, exec
	s_cselect_b32 s24, 0xffffffc0, 0
	v_cndmask_b32_e32 v1, 0, v204, vcc
	v_add_f32_e32 v0, v0, v1
	v_exp_f32_e32 v0, v0
	v_mov_b32_e32 v25, v144
	v_mov_b64_e32 v[22:23], s[8:9]
	v_ldexp_f32 v2, v0, s24
	v_sub_f32_e32 v4, 1.0, v2
	v_add_f32_e32 v0, -1.0, v4
	v_sub_f32_e32 v1, v0, v4
	v_add_f32_e32 v1, 1.0, v1
	v_sub_f32_e64 v0, -v2, v0
	v_add_f32_e32 v5, v0, v1
	v_frexp_mant_f32_e32 v0, v4
	v_cmp_gt_f32_e32 vcc, s77, v0
	v_cvt_f64_f32_e32 v[0:1], v4
	v_frexp_exp_i32_f64_e32 v0, v[0:1]
	v_subbrev_co_u32_e32 v10, vcc, 0, v0, vcc
	v_sub_u32_e32 v0, 0, v10
	v_ldexp_f32 v1, v4, v0
	v_add_f32_e32 v4, -1.0, v1
	v_add_f32_e32 v6, 1.0, v1
	v_ldexp_f32 v0, v5, v0
	v_add_f32_e32 v5, 1.0, v4
	v_add_f32_e32 v7, -1.0, v6
	v_sub_f32_e32 v5, v1, v5
	v_sub_f32_e32 v1, v1, v7
	v_add_f32_e32 v5, v0, v5
	v_add_f32_e32 v0, v0, v1
	v_add_f32_e32 v11, v6, v0
	v_rcp_f32_e32 v13, v11
	v_sub_f32_e32 v1, v11, v6
	v_sub_f32_e32 v12, v0, v1
	v_add_f32_e32 v1, v4, v5
	v_mul_f32_e32 v15, v1, v13
	v_sub_f32_e32 v0, v1, v4
	v_mul_f32_e32 v4, v11, v15
	v_fma_f32 v6, v15, v11, -v4
	v_fmac_f32_e32 v6, v15, v12
	v_sub_f32_e32 v14, v5, v0
	v_add_f32_e32 v0, v4, v6
	v_sub_f32_e32 v5, v1, v0
	v_pk_add_f32 v[8:9], v[0:1], v[4:5] neg_lo:[0,1] neg_hi:[0,1]
	v_mov_b32_e32 v7, v0
	v_pk_add_f32 v[0:1], v[8:9], v[6:7] neg_lo:[0,1] neg_hi:[0,1]
	v_cmp_nlt_f32_e32 vcc, 1.0, v2
	v_add_f32_e32 v1, v14, v1
	v_add_f32_e32 v0, v0, v1
	v_add_f32_e32 v1, v5, v0
	v_mul_f32_e32 v14, v13, v1
	v_mul_f32_e32 v4, v11, v14
	v_fma_f32 v6, v14, v11, -v4
	v_fmac_f32_e32 v6, v14, v12
	v_sub_f32_e32 v5, v5, v1
	v_add_f32_e32 v11, v0, v5
	v_add_f32_e32 v0, v4, v6
	v_sub_f32_e32 v5, v1, v0
	v_pk_add_f32 v[8:9], v[0:1], v[4:5] neg_lo:[0,1] neg_hi:[0,1]
	v_mov_b32_e32 v7, v0
	v_pk_add_f32 v[0:1], v[8:9], v[6:7] neg_lo:[0,1] neg_hi:[0,1]
	v_ashrrev_i32_e32 v36, 2, v25
	v_add_f32_e32 v1, v11, v1
	v_add_f32_e32 v0, v0, v1
	v_add_f32_e32 v1, v15, v14
	v_add_f32_e32 v0, v5, v0
	v_sub_f32_e32 v4, v1, v15
	v_mul_f32_e32 v0, v13, v0
	v_sub_f32_e32 v4, v14, v4
	v_add_f32_e32 v4, v4, v0
	v_add_f32_e32 v6, v1, v4
	v_mul_f32_e32 v7, v6, v6
	v_fmamk_f32 v0, v7, 0x3e9b6dac, v201
	v_fmaak_f32 v169, v7, v0, 0x3f2aaada
	v_cvt_f32_i32_e32 v0, v10
	v_sub_f32_e32 v1, v6, v1
	v_sub_f32_e32 v1, v4, v1
	v_ldexp_f32 v8, v1, 1
	v_mul_f32_e32 v1, v6, v7
	v_ldexp_f32 v5, v6, 1
	v_pk_mul_f32 v[6:7], v[0:1], v[168:169]
	s_lshl_b32 s24, s34, 7
	v_fma_f32 v4, v0, s94, -v6
	v_fmac_f32_e32 v4, 0xb102e308, v0
	v_pk_add_f32 v[0:1], v[6:7], v[4:5]
	s_nop 0
	v_sub_f32_e32 v5, v1, v5
	v_sub_f32_e32 v5, v7, v5
	v_add_f32_e32 v9, v8, v5
	v_mov_b32_e32 v8, v6
	v_pk_add_f32 v[6:7], v[0:1], v[6:7] neg_lo:[0,1] neg_hi:[0,1]
	v_pk_add_f32 v[10:11], v[0:1], v[8:9]
	v_mov_b32_e32 v5, v0
	v_mov_b32_e32 v7, v11
	v_pk_add_f32 v[12:13], v[4:5], v[6:7] neg_lo:[0,1] neg_hi:[0,1]
	v_pk_add_f32 v[4:5], v[4:5], v[6:7]
	v_mov_b32_e32 v16, v1
	v_pk_add_f32 v[6:7], v[4:5], v[0:1] op_sel:[1,0] op_sel_hi:[0,1] neg_lo:[0,1] neg_hi:[0,1]
	v_pk_add_f32 v[14:15], v[10:11], v[6:7] op_sel_hi:[1,0] neg_lo:[0,1] neg_hi:[0,1]
	v_mov_b32_e32 v10, v11
	v_mov_b32_e32 v11, v5
	v_mov_b32_e32 v17, v6
	v_pk_add_f32 v[6:7], v[10:11], v[16:17] neg_lo:[0,1] neg_hi:[0,1]
	v_mov_b32_e32 v8, v9
	v_mov_b32_e32 v9, v0
	v_pk_add_f32 v[0:1], v[8:9], v[6:7] neg_lo:[0,1] neg_hi:[0,1]
	v_mov_b32_e32 v14, v12
	v_pk_add_f32 v[6:7], v[14:15], v[0:1]
	v_mov_b32_e32 v13, v5
	v_pk_add_f32 v[8:9], v[6:7], v[6:7] op_sel:[0,1] op_sel_hi:[1,0]
	s_nop 0
	v_pk_add_f32 v[4:5], v[4:5], v[8:9] op_sel:[1,0] op_sel_hi:[0,1]
	v_mov_b32_e32 v7, v4
	v_pk_add_f32 v[10:11], v[6:7], v[12:13] neg_lo:[0,1] neg_hi:[0,1]
	v_mov_b32_e32 v1, v8
	v_sub_f32_e32 v5, v6, v10
	v_pk_add_f32 v[0:1], v[0:1], v[10:11] neg_lo:[0,1] neg_hi:[0,1]
	v_sub_f32_e32 v5, v12, v5
	v_add_f32_e32 v0, v0, v5
	v_add_f32_e32 v0, v0, v1
	v_add_f32_e32 v0, v4, v0
	v_cndmask_b32_e32 v0, v205, v0, vcc
	v_cmp_neq_f32_e32 vcc, 1.0, v2
	v_add_lshl_u32 v12, v36, s38, 5
	v_ashrrev_i32_e32 v13, 31, v12
	v_cndmask_b32_e32 v0, v206, v0, vcc
	v_cmp_gt_f32_e32 vcc, s95, v2
	v_lshlrev_b64 v[12:13], 2, v[12:13]
	s_nop 0
	v_cndmask_b32_e64 v35, v0, -v2, vcc
	v_lshlrev_b32_e32 v0, 3, v25
	v_and_b32_e32 v34, 24, v0
	v_lshlrev_b32_e32 v2, 2, v34
	v_lshl_add_u64 v[0:1], s[4:5], 0, v[2:3]
	v_lshl_add_u64 v[20:21], s[82:83], 0, v[2:3]
	v_lshl_add_u64 v[18:19], v[0:1], 0, v[12:13]
	v_lshl_add_u64 v[16:17], v[20:21], 0, v[12:13]
	v_sub_u32_e32 v12, 63, v36
	v_cvt_f32_i32_e32 v12, v12
	v_add_u32_e32 v2, s35, v36
	v_mad_i64_i32 v[4:5], s[40:41], v2, s72, v[22:23]
	v_mul_f32_e32 v12, v35, v12
	v_mul_f32_e32 v12, 0x3fb8aa3b, v12
	v_exp_f32_e32 v12, v12
	v_lshl_add_u64 v[4:5], v[4:5], 0, s[24:25]
	v_lshlrev_b32_e32 v2, 1, v34
	v_lshl_add_u64 v[4:5], v[4:5], 0, v[2:3]
	v_mov_b32_e32 v124, 0x18000
	v_mov_b32_e32 v125, 0
	v_lshl_add_u64 v[126:127], v[4:5], 0, v[124:125]
	global_load_dwordx4 v[8:11], v[4:5], off offset:2560
	s_nop 0
	global_load_dwordx4 v[4:7], v[4:5], off offset:2624
	v_mul_f32_e32 v24, 0x3e000000, v12
	global_load_dwordx4 v[12:15], v[18:19], off
	global_load_dwordx4 v[28:31], v[16:17], off
	global_load_dwordx4 v[178:181], v[18:19], off offset:16
	global_load_dwordx4 v[182:185], v[16:17], off offset:16
	global_load_dwordx4 v[100:103], v[126:127], off offset:2560
	global_load_dwordx4 v[104:107], v[126:127], off offset:2624
	v_lshl_add_u64 v[126:127], v[126:127], 0, v[124:125]
	global_load_dwordx4 v[108:111], v[126:127], off offset:2560
	global_load_dwordx4 v[112:115], v[126:127], off offset:2624
	v_lshl_add_u64 v[126:127], v[126:127], 0, v[124:125]
	global_load_dwordx4 v[116:119], v[126:127], off offset:2560
	global_load_dwordx4 v[120:123], v[126:127], off offset:2624
	s_waitcnt vmcnt(0) lgkmcnt(0)
; #define LAS __attribute__((address_space(3)))
; __device__ __forceinline__ u32x4 pack8(const float (&v)[8]) { u32x4 w; w.x = pk2(v[0], v[1]); w.y = pk2(v[2], v[3]); w.z = pk2(v[4], v[5]); w.w = pk2(v[6], v[7]); return w; }
; __device__ __forceinline__ void ld8bf(const bf16_t* p, float (&o)[8]) { unpack8(*(const u32x4*)p, o); }
; __device__ __forceinline__ void w_ret_m1(unsigned char* ws, const bf16_t* proj, LAS unsigned char* wl, int b, int ck_, int h, int lane) {
;     ...
;     for (int i = 0; i < 4; ++i) { const int m = (lane >> 2) + 16 * i, cp = lane & 3; float x1[8], x2[8];
;         const bf16_t* src = proj + (size_t)(row0 + m) * NIN + C_RK + 64 * h; ld8bf(src + 8 * cp, x1); ld8bf(src + 32 + 8 * cp, x2);
;         const float* cp_ = cosT + (64 * ck_ + m) * 32 + 8 * cp; const float* sp_ = sinT + (64 * ck_ + m) * 32 + 8 * cp;
;         const float sc = 0.125f * __expf((float)(63 - m) * lg);
;         float o1[8], o2[8];
; #pragma unroll
;         for (int j = 0; j < 8; ++j) { const float cs = cp_[j], sn = sp_[j]; o1[j] = (x1[j] * cs - x2[j] * sn) * sc; o2[j] = (x2[j] * cs + x1[j] * sn) * sc; }
;         *(LAS u32x4*)(kT + m * LD + 8 * cp) = pack8(o1); *(LAS u32x4*)(kT + m * LD + 32 + 8 * cp) = pack8(o2); }
	v_lshlrev_b32_e32 v32, 16, v8
	v_and_b32_e32 v33, 0xffff0000, v8
	v_lshlrev_b32_e32 v38, 16, v4
	v_and_b32_e32 v39, 0xffff0000, v4
	v_pk_mul_f32 v[26:27], v[28:29], v[32:33]
	v_pk_mul_f32 v[28:29], v[28:29], v[38:39]
	v_pk_fma_f32 v[26:27], v[12:13], v[38:39], v[26:27]
	v_pk_fma_f32 v[12:13], v[12:13], v[32:33], v[28:29] neg_lo:[0,0,1] neg_hi:[0,0,1]
	v_lshlrev_b32_e32 v8, 16, v9
	v_and_b32_e32 v9, 0xffff0000, v9
	v_pk_mul_f32 v[28:29], v[24:25], v[12:13] op_sel_hi:[0,1]
	v_lshlrev_b32_e32 v12, 16, v5
	v_and_b32_e32 v13, 0xffff0000, v5
	v_pk_mul_f32 v[4:5], v[30:31], v[8:9]
	v_lshlrev_b32_e32 v32, 16, v6
	v_pk_fma_f32 v[4:5], v[14:15], v[12:13], v[4:5]
	v_pk_mul_f32 v[12:13], v[30:31], v[12:13]
	v_lshlrev_b32_e32 v30, 16, v10
	v_pk_fma_f32 v[8:9], v[14:15], v[8:9], v[12:13] neg_lo:[0,0,1] neg_hi:[0,0,1]
	v_mov_b64_e32 v[12:13], v[178:179]
	v_mov_b64_e32 v[14:15], v[180:181]
	s_nop 0
	v_mov_b64_e32 v[16:17], v[182:183]
	v_mov_b64_e32 v[18:19], v[184:185]
	v_and_b32_e32 v31, 0xffff0000, v10
	v_and_b32_e32 v33, 0xffff0000, v6
	v_lshlrev_b32_e32 v10, 16, v11
	v_and_b32_e32 v11, 0xffff0000, v11
	v_lshlrev_b32_e32 v6, 16, v7
	v_and_b32_e32 v7, 0xffff0000, v7
	v_pk_mul_f32 v[8:9], v[24:25], v[8:9] op_sel_hi:[0,1]
	v_pk_mul_f32 v[4:5], v[24:25], v[4:5] op_sel_hi:[0,1]
	v_pk_mul_f32 v[26:27], v[24:25], v[26:27] op_sel_hi:[0,1]
	s_waitcnt vmcnt(0) lgkmcnt(0)
	v_pk_mul_f32 v[38:39], v[16:17], v[30:31]
	v_pk_mul_f32 v[16:17], v[16:17], v[32:33]
	v_pk_fma_f32 v[38:39], v[12:13], v[32:33], v[38:39]
	v_pk_fma_f32 v[12:13], v[12:13], v[30:31], v[16:17] neg_lo:[0,0,1] neg_hi:[0,0,1]
	v_pk_mul_f32 v[16:17], v[18:19], v[10:11]
	v_pk_mul_f32 v[12:13], v[24:25], v[12:13] op_sel_hi:[0,1]
	v_pk_fma_f32 v[16:17], v[14:15], v[6:7], v[16:17]
	v_pk_mul_f32 v[6:7], v[18:19], v[6:7]
	v_pk_mul_f32 v[38:39], v[24:25], v[38:39] op_sel_hi:[0,1]
	v_pk_fma_f32 v[6:7], v[14:15], v[10:11], v[6:7] neg_lo:[0,0,1] neg_hi:[0,0,1]
	v_pk_mul_f32 v[16:17], v[24:25], v[16:17] op_sel_hi:[0,1]
	v_pk_mul_f32 v[10:11], v[24:25], v[6:7] op_sel_hi:[0,1]
	v_cvt_pk_bf16_f32 v7, v8, v9
	v_cvt_pk_bf16_f32 v9, v10, v11
	v_mul_lo_u32 v10, v36, s23
	v_cvt_pk_bf16_f32 v6, v28, v29
	v_cvt_pk_bf16_f32 v8, v12, v13
	v_add3_u32 v18, s6, v10, v2
	v_add_u32_e32 v12, 16, v36
	ds_write_b128 v18, v[6:9] offset:9216
	v_cvt_pk_bf16_f32 v7, v4, v5
	v_add_u32_e32 v4, s35, v12
	v_mad_i64_i32 v[4:5], s[40:41], v4, s72, v[22:23]
	v_add_lshl_u32 v12, v12, s38, 5
	v_cvt_pk_bf16_f32 v6, v26, v27
	v_cvt_pk_bf16_f32 v8, v38, v39
	v_cvt_pk_bf16_f32 v9, v16, v17
	v_lshl_add_u64 v[4:5], v[4:5], 0, s[24:25]
	v_ashrrev_i32_e32 v13, 31, v12
	ds_write_b128 v18, v[6:9] offset:9280
	v_lshl_add_u64 v[4:5], v[4:5], 0, v[2:3]
	v_lshlrev_b64 v[12:13], 2, v[12:13]
	v_mov_b64_e32 v[8:9], v[100:101]
	v_mov_b64_e32 v[10:11], v[102:103]
	s_nop 0
	v_mov_b64_e32 v[4:5], v[104:105]
	v_mov_b64_e32 v[6:7], v[106:107]
	v_lshl_add_u64 v[38:39], v[0:1], 0, v[12:13]
	v_lshl_add_u64 v[40:41], v[20:21], 0, v[12:13]
	global_load_dwordx4 v[26:29], v[38:39], off
	global_load_dwordx4 v[30:33], v[40:41], off
	global_load_dwordx4 v[178:181], v[38:39], off offset:16
	global_load_dwordx4 v[182:185], v[40:41], off offset:16
	v_sub_u32_e32 v12, 47, v36
	v_cvt_f32_i32_e32 v12, v12
	v_mul_f32_e32 v12, v35, v12
	v_mul_f32_e32 v12, 0x3fb8aa3b, v12
	v_exp_f32_e32 v12, v12
	s_waitcnt vmcnt(0) lgkmcnt(0)
	v_lshlrev_b32_e32 v16, 16, v8
	v_and_b32_e32 v17, 0xffff0000, v8
	v_lshlrev_b32_e32 v42, 16, v4
	v_and_b32_e32 v43, 0xffff0000, v4
	v_pk_mul_f32 v[14:15], v[30:31], v[16:17]
	v_pk_mul_f32 v[30:31], v[30:31], v[42:43]
	v_lshlrev_b32_e32 v8, 16, v9
	v_and_b32_e32 v9, 0xffff0000, v9
	v_pk_fma_f32 v[14:15], v[26:27], v[42:43], v[14:15]
	v_pk_fma_f32 v[16:17], v[26:27], v[16:17], v[30:31] neg_lo:[0,0,1] neg_hi:[0,0,1]
	v_lshlrev_b32_e32 v26, 16, v5
	v_and_b32_e32 v27, 0xffff0000, v5
	v_pk_mul_f32 v[4:5], v[32:33], v[8:9]
	v_lshlrev_b32_e32 v42, 16, v10
	v_pk_fma_f32 v[4:5], v[28:29], v[26:27], v[4:5]
	v_pk_mul_f32 v[26:27], v[32:33], v[26:27]
	v_and_b32_e32 v43, 0xffff0000, v10
	v_pk_fma_f32 v[8:9], v[28:29], v[8:9], v[26:27] neg_lo:[0,0,1] neg_hi:[0,0,1]
	v_mov_b64_e32 v[26:27], v[178:179]
	v_mov_b64_e32 v[28:29], v[180:181]
	v_mov_b64_e32 v[30:31], v[182:183]
	v_mov_b64_e32 v[32:33], v[184:185]
	v_lshlrev_b32_e32 v44, 16, v6
	v_and_b32_e32 v45, 0xffff0000, v6
	v_lshlrev_b32_e32 v10, 16, v11
	v_and_b32_e32 v11, 0xffff0000, v11
	v_lshlrev_b32_e32 v6, 16, v7
	v_and_b32_e32 v7, 0xffff0000, v7
	v_mul_f32_e32 v12, 0x3e000000, v12
	v_pk_mul_f32 v[16:17], v[12:13], v[16:17] op_sel_hi:[0,1]
	v_pk_mul_f32 v[8:9], v[12:13], v[8:9] op_sel_hi:[0,1]
	v_pk_mul_f32 v[14:15], v[12:13], v[14:15] op_sel_hi:[0,1]
	v_pk_mul_f32 v[4:5], v[12:13], v[4:5] op_sel_hi:[0,1]
	s_waitcnt vmcnt(0) lgkmcnt(0)
; #define LAS __attribute__((address_space(3)))
; __device__ __forceinline__ u32x4 pack8(const float (&v)[8]) { u32x4 w; w.x = pk2(v[0], v[1]); w.y = pk2(v[2], v[3]); w.z = pk2(v[4], v[5]); w.w = pk2(v[6], v[7]); return w; }
; __device__ __forceinline__ void ld8bf(const bf16_t* p, float (&o)[8]) { unpack8(*(const u32x4*)p, o); }
; __device__ __forceinline__ void w_ret_m1(unsigned char* ws, const bf16_t* proj, LAS unsigned char* wl, int b, int ck_, int h, int lane) {
;     ...
;     for (int i = 0; i < 4; ++i) { const int m = (lane >> 2) + 16 * i, cp = lane & 3; float x1[8], x2[8];
;         const bf16_t* src = proj + (size_t)(row0 + m) * NIN + C_RK + 64 * h; ld8bf(src + 8 * cp, x1); ld8bf(src + 32 + 8 * cp, x2);
;         const float* cp_ = cosT + (64 * ck_ + m) * 32 + 8 * cp; const float* sp_ = sinT + (64 * ck_ + m) * 32 + 8 * cp;
;         const float sc = 0.125f * __expf((float)(63 - m) * lg);
;         float o1[8], o2[8];
; #pragma unroll
;         for (int j = 0; j < 8; ++j) { const float cs = cp_[j], sn = sp_[j]; o1[j] = (x1[j] * cs - x2[j] * sn) * sc; o2[j] = (x2[j] * cs + x1[j] * sn) * sc; }
;         *(LAS u32x4*)(kT + m * LD + 8 * cp) = pack8(o1); *(LAS u32x4*)(kT + m * LD + 32 + 8 * cp) = pack8(o2); }
;     w_store_vT(vT, proj + (size_t)row0 * NIN + C_RV + 64 * h, lane);
	v_pk_mul_f32 v[38:39], v[30:31], v[42:43]
	v_pk_mul_f32 v[30:31], v[30:31], v[44:45]
	v_pk_fma_f32 v[38:39], v[26:27], v[44:45], v[38:39]
	v_pk_fma_f32 v[26:27], v[26:27], v[42:43], v[30:31] neg_lo:[0,0,1] neg_hi:[0,0,1]
	v_pk_mul_f32 v[30:31], v[32:33], v[10:11]
	v_pk_mul_f32 v[26:27], v[12:13], v[26:27] op_sel_hi:[0,1]
	v_pk_fma_f32 v[30:31], v[28:29], v[6:7], v[30:31]
	v_pk_mul_f32 v[6:7], v[32:33], v[6:7]
	v_pk_mul_f32 v[38:39], v[12:13], v[38:39] op_sel_hi:[0,1]
	v_pk_fma_f32 v[6:7], v[28:29], v[10:11], v[6:7] neg_lo:[0,0,1] neg_hi:[0,0,1]
	v_pk_mul_f32 v[30:31], v[12:13], v[30:31] op_sel_hi:[0,1]
	v_pk_mul_f32 v[10:11], v[12:13], v[6:7] op_sel_hi:[0,1]
	v_cvt_pk_bf16_f32 v6, v16, v17
	v_cvt_pk_bf16_f32 v7, v8, v9
	v_cvt_pk_bf16_f32 v8, v26, v27
	v_cvt_pk_bf16_f32 v9, v10, v11
	v_add_u32_e32 v12, 32, v36
	ds_write_b128 v18, v[6:9] offset:11520
	v_cvt_pk_bf16_f32 v7, v4, v5
	v_add_u32_e32 v4, s35, v12
	v_mad_i64_i32 v[4:5], s[40:41], v4, s72, v[22:23]
	v_add_lshl_u32 v12, v12, s38, 5
	v_cvt_pk_bf16_f32 v6, v14, v15
	v_cvt_pk_bf16_f32 v8, v38, v39
	v_cvt_pk_bf16_f32 v9, v30, v31
	v_lshl_add_u64 v[4:5], v[4:5], 0, s[24:25]
	v_ashrrev_i32_e32 v13, 31, v12
	ds_write_b128 v18, v[6:9] offset:11584
	v_lshl_add_u64 v[4:5], v[4:5], 0, v[2:3]
	v_lshlrev_b64 v[12:13], 2, v[12:13]
	v_mov_b64_e32 v[8:9], v[108:109]
	v_mov_b64_e32 v[10:11], v[110:111]
	s_nop 0
	v_mov_b64_e32 v[4:5], v[112:113]
	v_mov_b64_e32 v[6:7], v[114:115]
	v_lshl_add_u64 v[38:39], v[0:1], 0, v[12:13]
	v_lshl_add_u64 v[40:41], v[20:21], 0, v[12:13]
	global_load_dwordx4 v[26:29], v[38:39], off
	global_load_dwordx4 v[30:33], v[40:41], off
	global_load_dwordx4 v[178:181], v[38:39], off offset:16
	global_load_dwordx4 v[182:185], v[40:41], off offset:16
	v_sub_u32_e32 v12, 31, v36
	v_cvt_f32_i32_e32 v12, v12
	v_mul_f32_e32 v12, v35, v12
	v_mul_f32_e32 v12, 0x3fb8aa3b, v12
	v_exp_f32_e32 v12, v12
	s_waitcnt vmcnt(0) lgkmcnt(0)
	v_lshlrev_b32_e32 v16, 16, v8
	v_and_b32_e32 v17, 0xffff0000, v8
	v_lshlrev_b32_e32 v42, 16, v4
	v_and_b32_e32 v43, 0xffff0000, v4
	v_pk_mul_f32 v[14:15], v[30:31], v[16:17]
	v_pk_mul_f32 v[30:31], v[30:31], v[42:43]
	v_lshlrev_b32_e32 v8, 16, v9
	v_and_b32_e32 v9, 0xffff0000, v9
	v_pk_fma_f32 v[14:15], v[26:27], v[42:43], v[14:15]
	v_pk_fma_f32 v[16:17], v[26:27], v[16:17], v[30:31] neg_lo:[0,0,1] neg_hi:[0,0,1]
	v_lshlrev_b32_e32 v26, 16, v5
	v_and_b32_e32 v27, 0xffff0000, v5
	v_pk_mul_f32 v[4:5], v[32:33], v[8:9]
	v_lshlrev_b32_e32 v42, 16, v10
	v_pk_fma_f32 v[4:5], v[28:29], v[26:27], v[4:5]
	v_pk_mul_f32 v[26:27], v[32:33], v[26:27]
	v_and_b32_e32 v43, 0xffff0000, v10
	v_pk_fma_f32 v[8:9], v[28:29], v[8:9], v[26:27] neg_lo:[0,0,1] neg_hi:[0,0,1]
	v_mov_b64_e32 v[26:27], v[178:179]
	v_mov_b64_e32 v[28:29], v[180:181]
	v_mov_b64_e32 v[30:31], v[182:183]
	v_mov_b64_e32 v[32:33], v[184:185]
	v_lshlrev_b32_e32 v44, 16, v6
	v_and_b32_e32 v45, 0xffff0000, v6
	v_lshlrev_b32_e32 v10, 16, v11
	v_and_b32_e32 v11, 0xffff0000, v11
	v_lshlrev_b32_e32 v6, 16, v7
	v_and_b32_e32 v7, 0xffff0000, v7
	v_mul_f32_e32 v12, 0x3e000000, v12
	v_pk_mul_f32 v[16:17], v[12:13], v[16:17] op_sel_hi:[0,1]
	v_pk_mul_f32 v[8:9], v[12:13], v[8:9] op_sel_hi:[0,1]
	v_pk_mul_f32 v[14:15], v[12:13], v[14:15] op_sel_hi:[0,1]
	v_pk_mul_f32 v[4:5], v[12:13], v[4:5] op_sel_hi:[0,1]
	s_waitcnt vmcnt(0) lgkmcnt(0)
	v_pk_mul_f32 v[38:39], v[30:31], v[42:43]
	v_pk_mul_f32 v[30:31], v[30:31], v[44:45]
	v_pk_fma_f32 v[38:39], v[26:27], v[44:45], v[38:39]
	v_pk_fma_f32 v[26:27], v[26:27], v[42:43], v[30:31] neg_lo:[0,0,1] neg_hi:[0,0,1]
	v_pk_mul_f32 v[30:31], v[32:33], v[10:11]
	v_pk_mul_f32 v[26:27], v[12:13], v[26:27] op_sel_hi:[0,1]
	v_pk_fma_f32 v[30:31], v[28:29], v[6:7], v[30:31]
	v_pk_mul_f32 v[6:7], v[32:33], v[6:7]
	v_pk_mul_f32 v[38:39], v[12:13], v[38:39] op_sel_hi:[0,1]
	v_pk_fma_f32 v[6:7], v[28:29], v[10:11], v[6:7] neg_lo:[0,0,1] neg_hi:[0,0,1]
	v_pk_mul_f32 v[30:31], v[12:13], v[30:31] op_sel_hi:[0,1]
	v_pk_mul_f32 v[10:11], v[12:13], v[6:7] op_sel_hi:[0,1]
	v_cvt_pk_bf16_f32 v6, v16, v17
	v_cvt_pk_bf16_f32 v7, v8, v9
	v_cvt_pk_bf16_f32 v8, v26, v27
	v_cvt_pk_bf16_f32 v9, v10, v11
	v_add_u32_e32 v12, 48, v36
	ds_write_b128 v18, v[6:9] offset:13824
	v_cvt_pk_bf16_f32 v7, v4, v5
	v_add_u32_e32 v4, s35, v12
	v_mad_i64_i32 v[4:5], s[40:41], v4, s72, v[22:23]
	v_add_lshl_u32 v12, v12, s38, 5
	v_cvt_pk_bf16_f32 v6, v14, v15
	v_cvt_pk_bf16_f32 v8, v38, v39
	v_cvt_pk_bf16_f32 v9, v30, v31
	v_lshl_add_u64 v[4:5], v[4:5], 0, s[24:25]
	v_ashrrev_i32_e32 v13, 31, v12
	ds_write_b128 v18, v[6:9] offset:13888
	v_lshl_add_u64 v[4:5], v[4:5], 0, v[2:3]
	v_lshlrev_b64 v[12:13], 2, v[12:13]
	v_mov_b64_e32 v[8:9], v[116:117]
	v_mov_b64_e32 v[10:11], v[118:119]
	s_nop 0
	v_mov_b64_e32 v[4:5], v[120:121]
	v_mov_b64_e32 v[6:7], v[122:123]
	v_lshl_add_u64 v[26:27], v[0:1], 0, v[12:13]
	v_lshl_add_u64 v[28:29], v[20:21], 0, v[12:13]
	global_load_dwordx4 v[14:17], v[26:27], off
	global_load_dwordx4 v[20:23], v[28:29], off
	global_load_dwordx4 v[178:181], v[26:27], off offset:16
	global_load_dwordx4 v[182:185], v[28:29], off offset:16
	v_sub_u32_e32 v0, 15, v36
	v_cvt_f32_i32_e32 v0, v0
	s_mul_hi_i32 s38, s35, 0x1800
	s_mulk_i32 s35, 0x1800
	s_add_u32 s35, s8, s35
	v_mul_f32_e32 v0, v35, v0
	v_mul_f32_e32 v0, 0x3fb8aa3b, v0
	v_exp_f32_e32 v0, v0
	s_addc_u32 s39, s9, s38
	s_add_u32 s38, s35, s24
	s_addc_u32 s39, s39, 0
	v_mul_f32_e32 v0, 0x3e000000, v0
	s_lshl_b32 s21, s21, 9
	s_lshl_b32 s24, s27, 2
	s_add_i32 s24, s24, s21
	s_or_b32 s34, s34, s24
	s_ashr_i32 s35, s34, 31
	s_lshl_b64 s[34:35], s[34:35], 13
	s_add_u32 s34, s67, s34
	s_addc_u32 s35, s28, s35
	s_waitcnt vmcnt(0) lgkmcnt(0)
; #define LAS __attribute__((address_space(3)))
; __device__ __forceinline__ unsigned pk2(float lo, float hi) { const f32x2_t v = {lo, hi}; const bf16x2_t b = __builtin_convertvector(v, bf16x2_t); return __builtin_bit_cast(unsigned, b); }
; __device__ __forceinline__ u32x4 pack8(const float (&v)[8]) { u32x4 w; w.x = pk2(v[0], v[1]); w.y = pk2(v[2], v[3]); w.z = pk2(v[4], v[5]); w.w = pk2(v[6], v[7]); return w; }
; #define WAVE_LDS_FENCE() asm volatile("s_waitcnt lgkmcnt(0)" ::: "memory")
; __device__ __forceinline__ void w_store_vT(LAS bf16_t* vN, const bf16_t* src, int lane) {
; #pragma unroll
;     for (int i = 0; i < 8; ++i) { const int m = (lane >> 3) + 8 * i, e0 = 8 * (lane & 7); *(LAS u32x4*)(vN + m * LD + e0) = *(const u32x4*)(src + (size_t)m * NIN + e0); }
; }
; __device__ __forceinline__ void w_kv(const LAS bf16_t* vN, const LAS bf16_t* kN, bf16_t* S, int lo, int fq) {
; #pragma unroll
;     for (int db = 0; db < 4; ++db) {
;         bf16x8 kf[2];
; #pragma unroll
;         for (int kk = 0; kk < 2; ++kk) kf[kk] = tr_frag(kN, 32 * kk + 8 * fq, 32 * kk + 8 * fq + 4, 16 * db, lo);
; #pragma unroll
;         for (int eb = 0; eb < 4; ++eb) { f32x4 acc = {0.f, 0.f, 0.f, 0.f};
; #pragma unroll
;             for (int kk = 0; kk < 2; ++kk) { const bf16x8 vf = tr_frag(vN, 32 * kk + 8 * fq, 32 * kk + 8 * fq + 4, 16 * eb, lo); acc = __builtin_amdgcn_mfma_f32_16x16x32_bf16(kf[kk], vf, acc, 0, 0, 0); }
;             *(unsigned long long*)(S + (16 * eb + lo) * 64 + 16 * db + 4 * fq) = (unsigned long long)pk2(acc[0], acc[1]) | ((unsigned long long)pk2(acc[2], acc[3]) << 32); }
;     }
; }
; __device__ __forceinline__ void w_ret_m1(unsigned char* ws, const bf16_t* proj, LAS unsigned char* wl, int b, int ck_, int h, int lane) {
;     ...
;         *(LAS u32x4*)(kT + m * LD + 8 * cp) = pack8(o1); *(LAS u32x4*)(kT + m * LD + 32 + 8 * cp) = pack8(o2); }
;     w_store_vT(vT, proj + (size_t)row0 * NIN + C_RV + 64 * h, lane);
;     WAVE_LDS_FENCE();
;     w_kv(vT, kT, (bf16_t*)(ws + WS_SRET) + (size_t)((b * NCH + ck_) * 4 + h) * 4096, lo, fq);
	v_lshlrev_b32_e32 v30, 16, v8
	v_and_b32_e32 v31, 0xffff0000, v8
	v_lshlrev_b32_e32 v32, 16, v4
	v_and_b32_e32 v33, 0xffff0000, v4
	v_pk_mul_f32 v[12:13], v[20:21], v[30:31]
	v_pk_mul_f32 v[20:21], v[20:21], v[32:33]
	v_lshlrev_b32_e32 v8, 16, v9
	v_and_b32_e32 v9, 0xffff0000, v9
	v_pk_fma_f32 v[12:13], v[14:15], v[32:33], v[12:13]
	v_pk_fma_f32 v[14:15], v[14:15], v[30:31], v[20:21] neg_lo:[0,0,1] neg_hi:[0,0,1]
	v_lshlrev_b32_e32 v20, 16, v5
	v_and_b32_e32 v21, 0xffff0000, v5
	v_pk_mul_f32 v[4:5], v[22:23], v[8:9]
	v_lshlrev_b32_e32 v30, 16, v6
	v_pk_fma_f32 v[4:5], v[16:17], v[20:21], v[4:5]
	v_pk_mul_f32 v[20:21], v[22:23], v[20:21]
	v_and_b32_e32 v31, 0xffff0000, v6
	v_pk_fma_f32 v[8:9], v[16:17], v[8:9], v[20:21] neg_lo:[0,0,1] neg_hi:[0,0,1]
	v_mov_b64_e32 v[20:21], v[178:179]
	v_mov_b64_e32 v[22:23], v[180:181]
	s_nop 0
	v_mov_b64_e32 v[26:27], v[182:183]
	v_mov_b64_e32 v[28:29], v[184:185]
	v_lshlrev_b32_e32 v16, 16, v10
	v_and_b32_e32 v17, 0xffff0000, v10
	v_lshlrev_b32_e32 v10, 16, v11
	v_and_b32_e32 v11, 0xffff0000, v11
	v_lshlrev_b32_e32 v6, 16, v7
	v_and_b32_e32 v7, 0xffff0000, v7
	v_pk_mul_f32 v[12:13], v[0:1], v[12:13] op_sel_hi:[0,1]
	v_pk_mul_f32 v[14:15], v[0:1], v[14:15] op_sel_hi:[0,1]
	v_pk_mul_f32 v[4:5], v[0:1], v[4:5] op_sel_hi:[0,1]
	v_pk_mul_f32 v[8:9], v[0:1], v[8:9] op_sel_hi:[0,1]
	s_waitcnt vmcnt(0) lgkmcnt(0)
	v_pk_mul_f32 v[32:33], v[26:27], v[16:17]
	v_pk_mul_f32 v[26:27], v[26:27], v[30:31]
	v_pk_fma_f32 v[32:33], v[20:21], v[30:31], v[32:33]
	v_pk_fma_f32 v[16:17], v[20:21], v[16:17], v[26:27] neg_lo:[0,0,1] neg_hi:[0,0,1]
	v_pk_mul_f32 v[20:21], v[28:29], v[10:11]
	v_pk_mul_f32 v[32:33], v[0:1], v[32:33] op_sel_hi:[0,1]
	v_pk_fma_f32 v[20:21], v[22:23], v[6:7], v[20:21]
	v_pk_mul_f32 v[6:7], v[28:29], v[6:7]
	v_pk_mul_f32 v[16:17], v[0:1], v[16:17] op_sel_hi:[0,1]
	v_pk_fma_f32 v[6:7], v[22:23], v[10:11], v[6:7] neg_lo:[0,0,1] neg_hi:[0,0,1]
	v_pk_mul_f32 v[20:21], v[0:1], v[20:21] op_sel_hi:[0,1]
	v_pk_mul_f32 v[0:1], v[0:1], v[6:7] op_sel_hi:[0,1]
	v_cvt_pk_bf16_f32 v6, v14, v15
	v_cvt_pk_bf16_f32 v7, v8, v9
	v_cvt_pk_bf16_f32 v8, v16, v17
	v_cvt_pk_bf16_f32 v9, v0, v1
	v_lshlrev_b32_e32 v0, 4, v25
	ds_write_b128 v18, v[6:9] offset:16128
	v_cvt_pk_bf16_f32 v6, v12, v13
	v_cvt_pk_bf16_f32 v7, v4, v5
	v_cvt_pk_bf16_f32 v8, v32, v33
	v_cvt_pk_bf16_f32 v9, v20, v21
	v_and_b32_e32 v2, 0x70, v0
	ds_write_b128 v18, v[6:9] offset:16192
	v_ashrrev_i32_e32 v9, 3, v25
	v_lshl_add_u64 v[0:1], s[38:39], 0, v[2:3]
	v_mad_i64_i32 v[4:5], s[38:39], v9, s72, v[0:1]
	global_load_dwordx4 v[224:227], v[4:5], off offset:3072
	v_add_u32_e32 v4, 8, v9
	v_mad_i64_i32 v[4:5], s[38:39], v4, s72, v[0:1]
	global_load_dwordx4 v[228:231], v[4:5], off offset:3072
	v_add_u32_e32 v4, 16, v9
	v_mad_i64_i32 v[4:5], s[38:39], v4, s72, v[0:1]
	global_load_dwordx4 v[232:235], v[4:5], off offset:3072
	v_add_u32_e32 v4, 24, v9
	v_mad_i64_i32 v[4:5], s[38:39], v4, s72, v[0:1]
	global_load_dwordx4 v[236:239], v[4:5], off offset:3072
	v_add_u32_e32 v4, 32, v9
	v_mad_i64_i32 v[4:5], s[38:39], v4, s72, v[0:1]
	global_load_dwordx4 v[240:243], v[4:5], off offset:3072
	v_add_u32_e32 v4, 40, v9
	v_mad_i64_i32 v[4:5], s[38:39], v4, s72, v[0:1]
	global_load_dwordx4 v[244:247], v[4:5], off offset:3072
	v_add_u32_e32 v4, 48, v9
	v_mad_i64_i32 v[4:5], s[38:39], v4, s72, v[0:1]
	global_load_dwordx4 v[248:251], v[4:5], off offset:3072
	v_add_u32_e32 v4, 56, v9
	v_mad_i64_i32 v[0:1], s[38:39], v4, s72, v[0:1]
	global_load_dwordx4 v[186:189], v[0:1], off offset:3072
	v_mul_lo_u32 v10, v9, s23
	v_add3_u32 v2, s6, v2, v10
	v_ashrrev_i32_e32 v8, 4, v25
	v_and_b32_e32 v17, 15, v25
	v_lshlrev_b32_e32 v0, 2, v8
	v_ashrrev_i32_e32 v1, 31, v0
	v_lshl_add_u64 v[0:1], v[0:1], 1, s[34:35]
	v_lshl_add_u64 v[26:27], v[0:1], 0, 32
	s_mov_b64 s[34:35], 0x60
	s_waitcnt vmcnt(0) lgkmcnt(0)
	ds_write_b128 v2, v[224:227]
	ds_write_b128 v2, v[228:231] offset:1152
	ds_write_b128 v2, v[232:235] offset:2304
	ds_write_b128 v2, v[236:239] offset:3456
	ds_write_b128 v2, v[240:243] offset:4608
	ds_write_b128 v2, v[244:247] offset:5760
	ds_write_b128 v2, v[248:251] offset:6912
	ds_write_b128 v2, v[186:189] offset:8064
	v_bfe_u32 v2, v25, 2, 2
	v_lshl_or_b32 v2, v8, 3, v2
	v_mul_lo_u32 v2, v2, s23
	s_waitcnt lgkmcnt(0)
	v_add3_u32 v16, s6, v34, v2
	ds_read_b64_tr_b16 v[8:9], v16 offset:9216
	ds_read_b64_tr_b16 v[10:11], v16 offset:9792
	ds_read_b64_tr_b16 v[4:5], v16 offset:13824
	ds_read_b64_tr_b16 v[6:7], v16 offset:14400
	ds_read_b64_tr_b16 v[12:13], v16
	ds_read_b64_tr_b16 v[14:15], v16 offset:576
	ds_read_b64_tr_b16 v[18:19], v16 offset:4608
	ds_read_b64_tr_b16 v[20:21], v16 offset:5184
	s_waitcnt lgkmcnt(2)
	v_mfma_f32_16x16x32_bf16 v[12:15], v[8:11], v[12:15], 0
	v_lshlrev_b32_e32 v2, 7, v17
	s_waitcnt lgkmcnt(0)
	v_mfma_f32_16x16x32_bf16 v[12:15], v[4:7], v[18:21], v[12:15]
	s_nop 7
	v_cvt_pk_bf16_f32 v18, v12, v13
	v_cvt_pk_bf16_f32 v19, v14, v15
	v_lshl_add_u64 v[12:13], v[0:1], 0, v[2:3]
	global_store_dwordx2 v[12:13], v[18:19], off
	ds_read_b64_tr_b16 v[18:19], v16 offset:32
	ds_read_b64_tr_b16 v[20:21], v16 offset:608
	ds_read_b64_tr_b16 v[22:23], v16 offset:4640
	ds_read_b64_tr_b16 v[24:25], v16 offset:5216
	s_waitcnt lgkmcnt(0)
	v_mfma_f32_16x16x32_bf16 v[18:21], v[8:11], v[18:21], 0
	v_mfma_f32_16x16x32_bf16 v[18:21], v[4:7], v[22:25], v[18:21]
	s_nop 7
	v_cvt_pk_bf16_f32 v14, v18, v19
	v_cvt_pk_bf16_f32 v15, v20, v21
	global_store_dwordx2 v[12:13], v[14:15], off offset:2048
	ds_read_b64_tr_b16 v[18:19], v16 offset:64
	ds_read_b64_tr_b16 v[20:21], v16 offset:640
	ds_read_b64_tr_b16 v[22:23], v16 offset:4672
	ds_read_b64_tr_b16 v[24:25], v16 offset:5248
	s_waitcnt lgkmcnt(0)
; #define LAS __attribute__((address_space(3)))
; __device__ __forceinline__ unsigned pk2(float lo, float hi) { const f32x2_t v = {lo, hi}; const bf16x2_t b = __builtin_convertvector(v, bf16x2_t); return __builtin_bit_cast(unsigned, b); }
; __device__ __forceinline__ void w_kv(const LAS bf16_t* vN, const LAS bf16_t* kN, bf16_t* S, int lo, int fq) {
; #pragma unroll
;     for (int db = 0; db < 4; ++db) {
;         bf16x8 kf[2];
; #pragma unroll
;         for (int kk = 0; kk < 2; ++kk) kf[kk] = tr_frag(kN, 32 * kk + 8 * fq, 32 * kk + 8 * fq + 4, 16 * db, lo);
; #pragma unroll
;         for (int eb = 0; eb < 4; ++eb) { f32x4 acc = {0.f, 0.f, 0.f, 0.f};
; #pragma unroll
;             for (int kk = 0; kk < 2; ++kk) { const bf16x8 vf = tr_frag(vN, 32 * kk + 8 * fq, 32 * kk + 8 * fq + 4, 16 * eb, lo); acc = __builtin_amdgcn_mfma_f32_16x16x32_bf16(kf[kk], vf, acc, 0, 0, 0); }
;             *(unsigned long long*)(S + (16 * eb + lo) * 64 + 16 * db + 4 * fq) = (unsigned long long)pk2(acc[0], acc[1]) | ((unsigned long long)pk2(acc[2], acc[3]) << 32); }
;     }
; }
	v_mfma_f32_16x16x32_bf16 v[18:21], v[8:11], v[18:21], 0
	v_or_b32_e32 v14, 0x1000, v2
	v_mov_b32_e32 v15, v3
	v_or_b32_e32 v2, 0x1800, v2
	v_mfma_f32_16x16x32_bf16 v[18:21], v[4:7], v[22:25], v[18:21]
	s_nop 7
	v_cvt_pk_bf16_f32 v18, v18, v19
	v_cvt_pk_bf16_f32 v19, v20, v21
	v_lshl_add_u64 v[20:21], v[0:1], 0, v[14:15]
	global_store_dwordx2 v[20:21], v[18:19], off
	ds_read_b64_tr_b16 v[18:19], v16 offset:96
	ds_read_b64_tr_b16 v[20:21], v16 offset:672
	s_waitcnt lgkmcnt(0)
	v_mfma_f32_16x16x32_bf16 v[8:11], v[8:11], v[18:21], 0
	ds_read_b64_tr_b16 v[18:19], v16 offset:4704
	ds_read_b64_tr_b16 v[20:21], v16 offset:5280
	s_waitcnt lgkmcnt(0)
	v_mfma_f32_16x16x32_bf16 v[4:7], v[4:7], v[18:21], v[8:11]
	s_nop 7
	v_cvt_pk_bf16_f32 v4, v4, v5
	v_cvt_pk_bf16_f32 v5, v6, v7
	v_lshl_add_u64 v[6:7], v[0:1], 0, v[2:3]
	global_store_dwordx2 v[6:7], v[4:5], off
	ds_read_b64_tr_b16 v[4:5], v16 offset:9248
	ds_read_b64_tr_b16 v[6:7], v16 offset:9824
	ds_read_b64_tr_b16 v[8:9], v16 offset:13856
	ds_read_b64_tr_b16 v[10:11], v16 offset:14432
	ds_read_b64_tr_b16 v[18:19], v16
	ds_read_b64_tr_b16 v[20:21], v16 offset:576
	ds_read_b64_tr_b16 v[22:23], v16 offset:4608
	ds_read_b64_tr_b16 v[24:25], v16 offset:5184
	s_waitcnt lgkmcnt(0)
	v_mfma_f32_16x16x32_bf16 v[18:21], v[4:7], v[18:21], 0
	v_mfma_f32_16x16x32_bf16 v[18:21], v[8:11], v[22:25], v[18:21]
	s_nop 7
	v_cvt_pk_bf16_f32 v18, v18, v19
	v_cvt_pk_bf16_f32 v19, v20, v21
	global_store_dwordx2 v[12:13], v[18:19], off offset:32
	ds_read_b64_tr_b16 v[18:19], v16 offset:32
	ds_read_b64_tr_b16 v[20:21], v16 offset:608
	ds_read_b64_tr_b16 v[22:23], v16 offset:4640
	ds_read_b64_tr_b16 v[24:25], v16 offset:5216
	s_waitcnt lgkmcnt(0)
	v_mfma_f32_16x16x32_bf16 v[18:21], v[4:7], v[18:21], 0
	v_mfma_f32_16x16x32_bf16 v[18:21], v[8:11], v[22:25], v[18:21]
	s_nop 7
	v_cvt_pk_bf16_f32 v18, v18, v19
	v_cvt_pk_bf16_f32 v19, v20, v21
	global_store_dwordx2 v[12:13], v[18:19], off offset:2080
	ds_read_b64_tr_b16 v[18:19], v16 offset:64
	ds_read_b64_tr_b16 v[20:21], v16 offset:640
	ds_read_b64_tr_b16 v[22:23], v16 offset:4672
	ds_read_b64_tr_b16 v[24:25], v16 offset:5248
	s_waitcnt lgkmcnt(0)
	v_mfma_f32_16x16x32_bf16 v[18:21], v[4:7], v[18:21], 0
	v_mfma_f32_16x16x32_bf16 v[18:21], v[8:11], v[22:25], v[18:21]
	s_nop 7
	v_cvt_pk_bf16_f32 v18, v18, v19
	v_cvt_pk_bf16_f32 v19, v20, v21
	v_lshl_add_u64 v[20:21], v[26:27], 0, v[14:15]
	global_store_dwordx2 v[20:21], v[18:19], off
	ds_read_b64_tr_b16 v[18:19], v16 offset:96
	ds_read_b64_tr_b16 v[20:21], v16 offset:672
	s_waitcnt lgkmcnt(0)
	v_mfma_f32_16x16x32_bf16 v[4:7], v[4:7], v[18:21], 0
	ds_read_b64_tr_b16 v[18:19], v16 offset:4704
	ds_read_b64_tr_b16 v[20:21], v16 offset:5280
	s_waitcnt lgkmcnt(0)
	v_mfma_f32_16x16x32_bf16 v[4:7], v[8:11], v[18:21], v[4:7]
	s_nop 7
	v_cvt_pk_bf16_f32 v4, v4, v5
	v_cvt_pk_bf16_f32 v5, v6, v7
	v_lshl_add_u64 v[6:7], v[26:27], 0, v[2:3]
	global_store_dwordx2 v[6:7], v[4:5], off
	ds_read_b64_tr_b16 v[4:5], v16 offset:9280
	ds_read_b64_tr_b16 v[6:7], v16 offset:9856
	ds_read_b64_tr_b16 v[8:9], v16 offset:13888
	ds_read_b64_tr_b16 v[10:11], v16 offset:14464
	ds_read_b64_tr_b16 v[18:19], v16
	ds_read_b64_tr_b16 v[20:21], v16 offset:576
	ds_read_b64_tr_b16 v[22:23], v16 offset:4608
	ds_read_b64_tr_b16 v[24:25], v16 offset:5184
	s_waitcnt lgkmcnt(0)
	v_mfma_f32_16x16x32_bf16 v[18:21], v[4:7], v[18:21], 0
	v_lshl_add_u64 v[26:27], v[0:1], 0, 64
	v_lshl_add_u64 v[0:1], v[0:1], 0, s[34:35]
	v_mfma_f32_16x16x32_bf16 v[18:21], v[8:11], v[22:25], v[18:21]
	s_nop 7
	v_cvt_pk_bf16_f32 v18, v18, v19
	v_cvt_pk_bf16_f32 v19, v20, v21
	global_store_dwordx2 v[12:13], v[18:19], off offset:64
	ds_read_b64_tr_b16 v[18:19], v16 offset:32
	ds_read_b64_tr_b16 v[20:21], v16 offset:608
	ds_read_b64_tr_b16 v[22:23], v16 offset:4640
	ds_read_b64_tr_b16 v[24:25], v16 offset:5216
	s_waitcnt lgkmcnt(0)
; #define LAS __attribute__((address_space(3)))
; __device__ __forceinline__ unsigned pk2(float lo, float hi) { const f32x2_t v = {lo, hi}; const bf16x2_t b = __builtin_convertvector(v, bf16x2_t); return __builtin_bit_cast(unsigned, b); }
; __device__ __forceinline__ void w_kv(const LAS bf16_t* vN, const LAS bf16_t* kN, bf16_t* S, int lo, int fq) {
; #pragma unroll
;     for (int db = 0; db < 4; ++db) {
;         bf16x8 kf[2];
; #pragma unroll
;         for (int kk = 0; kk < 2; ++kk) kf[kk] = tr_frag(kN, 32 * kk + 8 * fq, 32 * kk + 8 * fq + 4, 16 * db, lo);
; #pragma unroll
;         for (int eb = 0; eb < 4; ++eb) { f32x4 acc = {0.f, 0.f, 0.f, 0.f};
; #pragma unroll
;             for (int kk = 0; kk < 2; ++kk) { const bf16x8 vf = tr_frag(vN, 32 * kk + 8 * fq, 32 * kk + 8 * fq + 4, 16 * eb, lo); acc = __builtin_amdgcn_mfma_f32_16x16x32_bf16(kf[kk], vf, acc, 0, 0, 0); }
;             *(unsigned long long*)(S + (16 * eb + lo) * 64 + 16 * db + 4 * fq) = (unsigned long long)pk2(acc[0], acc[1]) | ((unsigned long long)pk2(acc[2], acc[3]) << 32); }
;     }
; }
	v_mfma_f32_16x16x32_bf16 v[18:21], v[4:7], v[18:21], 0
	v_mfma_f32_16x16x32_bf16 v[18:21], v[8:11], v[22:25], v[18:21]
	s_nop 7
	v_cvt_pk_bf16_f32 v18, v18, v19
	v_cvt_pk_bf16_f32 v19, v20, v21
	global_store_dwordx2 v[12:13], v[18:19], off offset:2112
	ds_read_b64_tr_b16 v[18:19], v16 offset:64
	ds_read_b64_tr_b16 v[20:21], v16 offset:640
	ds_read_b64_tr_b16 v[22:23], v16 offset:4672
	ds_read_b64_tr_b16 v[24:25], v16 offset:5248
	s_waitcnt lgkmcnt(0)
	v_mfma_f32_16x16x32_bf16 v[18:21], v[4:7], v[18:21], 0
	v_mfma_f32_16x16x32_bf16 v[18:21], v[8:11], v[22:25], v[18:21]
	s_nop 7
	v_cvt_pk_bf16_f32 v18, v18, v19
	v_cvt_pk_bf16_f32 v19, v20, v21
	v_lshl_add_u64 v[20:21], v[26:27], 0, v[14:15]
	global_store_dwordx2 v[20:21], v[18:19], off
	ds_read_b64_tr_b16 v[18:19], v16 offset:96
	ds_read_b64_tr_b16 v[20:21], v16 offset:672
	s_waitcnt lgkmcnt(0)
	v_mfma_f32_16x16x32_bf16 v[4:7], v[4:7], v[18:21], 0
	ds_read_b64_tr_b16 v[18:19], v16 offset:4704
	ds_read_b64_tr_b16 v[20:21], v16 offset:5280
	v_lshl_add_u64 v[14:15], v[0:1], 0, v[14:15]
	v_lshl_add_u64 v[0:1], v[0:1], 0, v[2:3]
	s_waitcnt lgkmcnt(0)
	v_mfma_f32_16x16x32_bf16 v[4:7], v[8:11], v[18:21], v[4:7]
	s_nop 7
	v_cvt_pk_bf16_f32 v4, v4, v5
	v_cvt_pk_bf16_f32 v5, v6, v7
	v_lshl_add_u64 v[6:7], v[26:27], 0, v[2:3]
	global_store_dwordx2 v[6:7], v[4:5], off
	ds_read_b64_tr_b16 v[4:5], v16 offset:9312
	ds_read_b64_tr_b16 v[6:7], v16 offset:9888
	ds_read_b64_tr_b16 v[8:9], v16 offset:13920
	ds_read_b64_tr_b16 v[10:11], v16 offset:14496
	ds_read_b64_tr_b16 v[18:19], v16
	ds_read_b64_tr_b16 v[20:21], v16 offset:576
	ds_read_b64_tr_b16 v[22:23], v16 offset:4608
	ds_read_b64_tr_b16 v[24:25], v16 offset:5184
	s_waitcnt lgkmcnt(0)
	v_mfma_f32_16x16x32_bf16 v[18:21], v[4:7], v[18:21], 0
	v_mfma_f32_16x16x32_bf16 v[18:21], v[8:11], v[22:25], v[18:21]
	s_nop 7
	v_cvt_pk_bf16_f32 v18, v18, v19
	v_cvt_pk_bf16_f32 v19, v20, v21
	global_store_dwordx2 v[12:13], v[18:19], off offset:96
	ds_read_b64_tr_b16 v[18:19], v16 offset:32
	ds_read_b64_tr_b16 v[20:21], v16 offset:608
	ds_read_b64_tr_b16 v[22:23], v16 offset:4640
	ds_read_b64_tr_b16 v[24:25], v16 offset:5216
	s_waitcnt lgkmcnt(0)
	v_mfma_f32_16x16x32_bf16 v[18:21], v[4:7], v[18:21], 0
	v_mfma_f32_16x16x32_bf16 v[18:21], v[8:11], v[22:25], v[18:21]
	s_nop 7
	v_cvt_pk_bf16_f32 v18, v18, v19
	v_cvt_pk_bf16_f32 v19, v20, v21
	global_store_dwordx2 v[12:13], v[18:19], off offset:2144
	ds_read_b64_tr_b16 v[18:19], v16 offset:64
	ds_read_b64_tr_b16 v[20:21], v16 offset:640
	ds_read_b64_tr_b16 v[22:23], v16 offset:4672
	ds_read_b64_tr_b16 v[24:25], v16 offset:5248
	s_waitcnt lgkmcnt(0)
	v_mfma_f32_16x16x32_bf16 v[18:21], v[4:7], v[18:21], 0
	v_mfma_f32_16x16x32_bf16 v[18:21], v[8:11], v[22:25], v[18:21]
	s_nop 7
	v_cvt_pk_bf16_f32 v12, v18, v19
	v_cvt_pk_bf16_f32 v13, v20, v21
	global_store_dwordx2 v[14:15], v[12:13], off
	ds_read_b64_tr_b16 v[12:13], v16 offset:96
	ds_read_b64_tr_b16 v[14:15], v16 offset:672
	s_waitcnt lgkmcnt(0)
	v_mfma_f32_16x16x32_bf16 v[4:7], v[4:7], v[12:15], 0
	ds_read_b64_tr_b16 v[12:13], v16 offset:4704
	ds_read_b64_tr_b16 v[14:15], v16 offset:5280
	s_waitcnt lgkmcnt(0)
	v_mfma_f32_16x16x32_bf16 v[4:7], v[8:11], v[12:15], v[4:7]
	s_nop 7
	v_cvt_pk_bf16_f32 v4, v4, v5
	v_cvt_pk_bf16_f32 v5, v6, v7
	global_store_dwordx2 v[0:1], v[4:5], off
	s_waitcnt lgkmcnt(0)
	s_branch .LBB0_515

; #define LAS __attribute__((address_space(3)))
; __device__ __forceinline__ unsigned pk2(float lo, float hi) { const f32x2_t v = {lo, hi}; const bf16x2_t b = __builtin_convertvector(v, bf16x2_t); return __builtin_bit_cast(unsigned, b); }
; #define WAVE_LDS_FENCE() asm volatile("s_waitcnt lgkmcnt(0)" ::: "memory")
; __device__ __forceinline__ void w_store_vT(LAS bf16_t* vN, const bf16_t* src, int lane) {
; #pragma unroll
;     for (int i = 0; i < 8; ++i) { const int m = (lane >> 3) + 8 * i, e0 = 8 * (lane & 7); *(LAS u32x4*)(vN + m * LD + e0) = *(const u32x4*)(src + (size_t)m * NIN + e0); }
; }
; __device__ __forceinline__ void w_kv(const LAS bf16_t* vN, const LAS bf16_t* kN, bf16_t* S, int lo, int fq) {
; #pragma unroll
;     for (int db = 0; db < 4; ++db) {
;         bf16x8 kf[2];
; #pragma unroll
;         for (int kk = 0; kk < 2; ++kk) kf[kk] = tr_frag(kN, 32 * kk + 8 * fq, 32 * kk + 8 * fq + 4, 16 * db, lo);
; #pragma unroll
;         for (int eb = 0; eb < 4; ++eb) { f32x4 acc = {0.f, 0.f, 0.f, 0.f};
; #pragma unroll
;             for (int kk = 0; kk < 2; ++kk) { const bf16x8 vf = tr_frag(vN, 32 * kk + 8 * fq, 32 * kk + 8 * fq + 4, 16 * eb, lo); acc = __builtin_amdgcn_mfma_f32_16x16x32_bf16(kf[kk], vf, acc, 0, 0, 0); }
;             *(unsigned long long*)(S + (16 * eb + lo) * 64 + 16 * db + 4 * fq) = (unsigned long long)pk2(acc[0], acc[1]) | ((unsigned long long)pk2(acc[2], acc[3]) << 32); }
;     }
; }
; __device__ __forceinline__ void w_hg_m1(const Args& a, int l, unsigned char* ws, const bf16_t* proj, LAS unsigned char* wl, int b, int ck_, int h, int lane) {
;     ...
;     w_store_vT(vT, proj + (size_t)row0 * NIN + C_HI + 64 * h, lane);
;     WAVE_LDS_FENCE();
;     w_kv(vT, kT, (bf16_t*)(ws + WS_SHG) + (size_t)((b * NCH + ck_) * 4 + h) * 4096, lo, fq);
;     WAVE_LDS_FENCE();
.LBB0_529:
	s_or_b64 exec, exec, s[34:35]
	s_add_u32 s20, s91, s93
	v_lshlrev_b32_e32 v2, 4, v33
	s_addc_u32 s21, s92, 0
	v_and_b32_e32 v2, 0x70, v2
	v_lshl_add_u64 v[4:5], s[20:21], 0, v[2:3]
	s_mov_b64 s[20:21], 0x1400
	v_ashrrev_i32_e32 v1, 3, v33
	v_lshl_add_u64 v[8:9], v[4:5], 0, s[20:21]
	v_mad_i64_i32 v[4:5], s[20:21], v1, s72, v[8:9]
	global_load_dwordx4 v[224:227], v[4:5], off
	v_add_u32_e32 v4, 8, v1
	v_mad_i64_i32 v[4:5], s[20:21], v4, s72, v[8:9]
	global_load_dwordx4 v[228:231], v[4:5], off
	v_add_u32_e32 v4, 16, v1
	v_mad_i64_i32 v[4:5], s[20:21], v4, s72, v[8:9]
	global_load_dwordx4 v[232:235], v[4:5], off
	v_add_u32_e32 v4, 24, v1
	v_mad_i64_i32 v[4:5], s[20:21], v4, s72, v[8:9]
	global_load_dwordx4 v[236:239], v[4:5], off
	v_add_u32_e32 v4, 32, v1
	v_mad_i64_i32 v[4:5], s[20:21], v4, s72, v[8:9]
	global_load_dwordx4 v[240:243], v[4:5], off
	v_add_u32_e32 v4, 40, v1
	v_mad_i64_i32 v[4:5], s[20:21], v4, s72, v[8:9]
	global_load_dwordx4 v[244:247], v[4:5], off
	v_add_u32_e32 v4, 48, v1
	v_mad_i64_i32 v[4:5], s[20:21], v4, s72, v[8:9]
	global_load_dwordx4 v[248:251], v[4:5], off
	v_add_u32_e32 v4, 56, v1
	v_mad_i64_i32 v[4:5], s[20:21], v4, s72, v[8:9]
	global_load_dwordx4 v[186:189], v[4:5], off
	v_mul_lo_u32 v10, v1, s23
	v_add3_u32 v2, s6, v2, v10
	s_lshl_b64 s[20:21], s[62:63], 13
	s_add_u32 s20, s7, s20
	s_addc_u32 s21, s66, s21
	v_lshrrev_b32_e32 v1, 2, v34
	s_waitcnt vmcnt(0) lgkmcnt(0)
	ds_write_b128 v2, v[224:227]
	ds_write_b128 v2, v[228:231] offset:1152
	ds_write_b128 v2, v[232:235] offset:2304
	ds_write_b128 v2, v[236:239] offset:3456
	ds_write_b128 v2, v[240:243] offset:4608
	ds_write_b128 v2, v[244:247] offset:5760
	ds_write_b128 v2, v[248:251] offset:6912
	ds_write_b128 v2, v[186:189] offset:8064
	v_lshlrev_b32_e32 v2, 3, v34
	v_lshlrev_b32_e32 v4, 2, v32
	v_and_b32_e32 v2, 24, v2
	v_ashrrev_i32_e32 v5, 31, v4
	v_add_u32_e32 v2, s6, v2
	v_lshl_add_u64 v[6:7], v[4:5], 1, s[20:21]
	v_or_b32_e32 v4, v0, v1
	v_add_u32_e32 v0, v0, v1
	s_waitcnt lgkmcnt(0)
	v_mad_u64_u32 v[4:5], s[20:21], v4, s23, v[2:3]
	v_mad_u64_u32 v[0:1], s[20:21], v0, s23, v[2:3]
	ds_read_b64_tr_b16 v[12:13], v4 offset:9216
	ds_read_b64_tr_b16 v[14:15], v4 offset:9792
	ds_read_b64_tr_b16 v[16:17], v0 offset:13824
	ds_read_b64_tr_b16 v[18:19], v0 offset:14400
	ds_read_b64_tr_b16 v[8:9], v4
	ds_read_b64_tr_b16 v[10:11], v4 offset:576
	ds_read_b64_tr_b16 v[20:21], v0 offset:4608
	ds_read_b64_tr_b16 v[22:23], v0 offset:5184
	s_waitcnt lgkmcnt(2)
	v_mfma_f32_16x16x32_bf16 v[8:11], v[12:15], v[8:11], 0
	v_lshlrev_b32_e32 v2, 7, v34
	v_lshl_add_u64 v[28:29], v[6:7], 0, 32
	s_mov_b64 s[20:21], 0x60
	s_waitcnt lgkmcnt(0)
	v_mfma_f32_16x16x32_bf16 v[8:11], v[16:19], v[20:23], v[8:11]
	s_nop 7
	v_cvt_pk_bf16_f32 v20, v8, v9
	v_cvt_pk_bf16_f32 v21, v10, v11
	v_lshl_add_u64 v[8:9], v[6:7], 0, v[2:3]
	global_store_dwordx2 v[8:9], v[20:21], off
	ds_read_b64_tr_b16 v[20:21], v4 offset:32
	ds_read_b64_tr_b16 v[22:23], v4 offset:608
	ds_read_b64_tr_b16 v[24:25], v0 offset:4640
	ds_read_b64_tr_b16 v[26:27], v0 offset:5216
	s_waitcnt lgkmcnt(0)
	v_mfma_f32_16x16x32_bf16 v[20:23], v[12:15], v[20:23], 0
	v_mfma_f32_16x16x32_bf16 v[20:23], v[16:19], v[24:27], v[20:23]
	s_nop 7
	v_cvt_pk_bf16_f32 v10, v20, v21
	v_cvt_pk_bf16_f32 v11, v22, v23
	global_store_dwordx2 v[8:9], v[10:11], off offset:2048
	ds_read_b64_tr_b16 v[20:21], v4 offset:64
	ds_read_b64_tr_b16 v[22:23], v4 offset:640
	ds_read_b64_tr_b16 v[24:25], v0 offset:4672
	ds_read_b64_tr_b16 v[26:27], v0 offset:5248
	s_waitcnt lgkmcnt(0)
	v_mfma_f32_16x16x32_bf16 v[20:23], v[12:15], v[20:23], 0
	v_or_b32_e32 v10, 0x1000, v2
	v_mov_b32_e32 v11, v3
	v_or_b32_e32 v2, 0x1800, v2
	v_mfma_f32_16x16x32_bf16 v[20:23], v[16:19], v[24:27], v[20:23]
	s_nop 7
	v_cvt_pk_bf16_f32 v20, v20, v21
	v_cvt_pk_bf16_f32 v21, v22, v23
	v_lshl_add_u64 v[22:23], v[6:7], 0, v[10:11]
	global_store_dwordx2 v[22:23], v[20:21], off
	ds_read_b64_tr_b16 v[20:21], v4 offset:96
	ds_read_b64_tr_b16 v[22:23], v4 offset:672
	s_waitcnt lgkmcnt(0)
	v_mfma_f32_16x16x32_bf16 v[12:15], v[12:15], v[20:23], 0
	ds_read_b64_tr_b16 v[20:21], v0 offset:4704
	ds_read_b64_tr_b16 v[22:23], v0 offset:5280
	s_waitcnt lgkmcnt(0)
	v_mfma_f32_16x16x32_bf16 v[12:15], v[16:19], v[20:23], v[12:15]
	s_nop 7
	v_cvt_pk_bf16_f32 v12, v12, v13
	v_cvt_pk_bf16_f32 v13, v14, v15
	v_lshl_add_u64 v[14:15], v[6:7], 0, v[2:3]
	global_store_dwordx2 v[14:15], v[12:13], off
	ds_read_b64_tr_b16 v[12:13], v4 offset:9248
	ds_read_b64_tr_b16 v[14:15], v4 offset:9824
	ds_read_b64_tr_b16 v[16:17], v0 offset:13856
	ds_read_b64_tr_b16 v[18:19], v0 offset:14432
	ds_read_b64_tr_b16 v[20:21], v4
	ds_read_b64_tr_b16 v[22:23], v4 offset:576
	ds_read_b64_tr_b16 v[24:25], v0 offset:4608
	ds_read_b64_tr_b16 v[26:27], v0 offset:5184
	s_waitcnt lgkmcnt(0)
	v_mfma_f32_16x16x32_bf16 v[20:23], v[12:15], v[20:23], 0
	v_mfma_f32_16x16x32_bf16 v[20:23], v[16:19], v[24:27], v[20:23]
	s_nop 7
	v_cvt_pk_bf16_f32 v20, v20, v21
	v_cvt_pk_bf16_f32 v21, v22, v23
	global_store_dwordx2 v[8:9], v[20:21], off offset:32
	ds_read_b64_tr_b16 v[20:21], v4 offset:32
	ds_read_b64_tr_b16 v[22:23], v4 offset:608
	ds_read_b64_tr_b16 v[24:25], v0 offset:4640
	ds_read_b64_tr_b16 v[26:27], v0 offset:5216
	s_waitcnt lgkmcnt(0)
; #define LAS __attribute__((address_space(3)))
; __device__ __forceinline__ unsigned pk2(float lo, float hi) { const f32x2_t v = {lo, hi}; const bf16x2_t b = __builtin_convertvector(v, bf16x2_t); return __builtin_bit_cast(unsigned, b); }
; __device__ __forceinline__ void w_kv(const LAS bf16_t* vN, const LAS bf16_t* kN, bf16_t* S, int lo, int fq) {
; #pragma unroll
;     for (int db = 0; db < 4; ++db) {
;         bf16x8 kf[2];
; #pragma unroll
;         for (int kk = 0; kk < 2; ++kk) kf[kk] = tr_frag(kN, 32 * kk + 8 * fq, 32 * kk + 8 * fq + 4, 16 * db, lo);
; #pragma unroll
;         for (int eb = 0; eb < 4; ++eb) { f32x4 acc = {0.f, 0.f, 0.f, 0.f};
; #pragma unroll
;             for (int kk = 0; kk < 2; ++kk) { const bf16x8 vf = tr_frag(vN, 32 * kk + 8 * fq, 32 * kk + 8 * fq + 4, 16 * eb, lo); acc = __builtin_amdgcn_mfma_f32_16x16x32_bf16(kf[kk], vf, acc, 0, 0, 0); }
;             *(unsigned long long*)(S + (16 * eb + lo) * 64 + 16 * db + 4 * fq) = (unsigned long long)pk2(acc[0], acc[1]) | ((unsigned long long)pk2(acc[2], acc[3]) << 32); }
;     }
; }
	v_mfma_f32_16x16x32_bf16 v[20:23], v[12:15], v[20:23], 0
	v_mfma_f32_16x16x32_bf16 v[20:23], v[16:19], v[24:27], v[20:23]
	s_nop 7
	v_cvt_pk_bf16_f32 v20, v20, v21
	v_cvt_pk_bf16_f32 v21, v22, v23
	global_store_dwordx2 v[8:9], v[20:21], off offset:2080
	ds_read_b64_tr_b16 v[20:21], v4 offset:64
	ds_read_b64_tr_b16 v[22:23], v4 offset:640
	ds_read_b64_tr_b16 v[24:25], v0 offset:4672
	ds_read_b64_tr_b16 v[26:27], v0 offset:5248
	s_waitcnt lgkmcnt(0)
	v_mfma_f32_16x16x32_bf16 v[20:23], v[12:15], v[20:23], 0
	v_mfma_f32_16x16x32_bf16 v[20:23], v[16:19], v[24:27], v[20:23]
	s_nop 7
	v_cvt_pk_bf16_f32 v20, v20, v21
	v_cvt_pk_bf16_f32 v21, v22, v23
	v_lshl_add_u64 v[22:23], v[28:29], 0, v[10:11]
	global_store_dwordx2 v[22:23], v[20:21], off
	ds_read_b64_tr_b16 v[20:21], v4 offset:96
	ds_read_b64_tr_b16 v[22:23], v4 offset:672
	s_waitcnt lgkmcnt(0)
	v_mfma_f32_16x16x32_bf16 v[12:15], v[12:15], v[20:23], 0
	ds_read_b64_tr_b16 v[20:21], v0 offset:4704
	ds_read_b64_tr_b16 v[22:23], v0 offset:5280
	s_waitcnt lgkmcnt(0)
	v_mfma_f32_16x16x32_bf16 v[12:15], v[16:19], v[20:23], v[12:15]
	s_nop 7
	v_cvt_pk_bf16_f32 v12, v12, v13
	v_cvt_pk_bf16_f32 v13, v14, v15
	v_lshl_add_u64 v[14:15], v[28:29], 0, v[2:3]
	global_store_dwordx2 v[14:15], v[12:13], off
	ds_read_b64_tr_b16 v[12:13], v4 offset:9280
	ds_read_b64_tr_b16 v[14:15], v4 offset:9856
	ds_read_b64_tr_b16 v[16:17], v0 offset:13888
	ds_read_b64_tr_b16 v[18:19], v0 offset:14464
	ds_read_b64_tr_b16 v[20:21], v4
	ds_read_b64_tr_b16 v[22:23], v4 offset:576
	ds_read_b64_tr_b16 v[24:25], v0 offset:4608
	ds_read_b64_tr_b16 v[26:27], v0 offset:5184
	s_waitcnt lgkmcnt(0)
	v_mfma_f32_16x16x32_bf16 v[20:23], v[12:15], v[20:23], 0
	v_lshl_add_u64 v[28:29], v[6:7], 0, 64
	v_mfma_f32_16x16x32_bf16 v[20:23], v[16:19], v[24:27], v[20:23]
	s_nop 7
	v_cvt_pk_bf16_f32 v20, v20, v21
	v_cvt_pk_bf16_f32 v21, v22, v23
	global_store_dwordx2 v[8:9], v[20:21], off offset:64
	ds_read_b64_tr_b16 v[20:21], v4 offset:32
	ds_read_b64_tr_b16 v[22:23], v4 offset:608
	ds_read_b64_tr_b16 v[24:25], v0 offset:4640
	ds_read_b64_tr_b16 v[26:27], v0 offset:5216
	s_waitcnt lgkmcnt(0)
	v_mfma_f32_16x16x32_bf16 v[20:23], v[12:15], v[20:23], 0
	v_mfma_f32_16x16x32_bf16 v[20:23], v[16:19], v[24:27], v[20:23]
	s_nop 7
	v_cvt_pk_bf16_f32 v20, v20, v21
	v_cvt_pk_bf16_f32 v21, v22, v23
	global_store_dwordx2 v[8:9], v[20:21], off offset:2112
	ds_read_b64_tr_b16 v[20:21], v4 offset:64
	ds_read_b64_tr_b16 v[22:23], v4 offset:640
	ds_read_b64_tr_b16 v[24:25], v0 offset:4672
	ds_read_b64_tr_b16 v[26:27], v0 offset:5248
	s_waitcnt lgkmcnt(0)
	v_mfma_f32_16x16x32_bf16 v[20:23], v[12:15], v[20:23], 0
	v_mfma_f32_16x16x32_bf16 v[20:23], v[16:19], v[24:27], v[20:23]
	s_nop 7
	v_cvt_pk_bf16_f32 v20, v20, v21
	v_cvt_pk_bf16_f32 v21, v22, v23
	v_lshl_add_u64 v[22:23], v[28:29], 0, v[10:11]
	global_store_dwordx2 v[22:23], v[20:21], off
	ds_read_b64_tr_b16 v[20:21], v4 offset:96
	ds_read_b64_tr_b16 v[22:23], v4 offset:672
	s_waitcnt lgkmcnt(0)
	v_mfma_f32_16x16x32_bf16 v[12:15], v[12:15], v[20:23], 0
	ds_read_b64_tr_b16 v[20:21], v0 offset:4704
	ds_read_b64_tr_b16 v[22:23], v0 offset:5280
	s_waitcnt lgkmcnt(0)
	v_mfma_f32_16x16x32_bf16 v[12:15], v[16:19], v[20:23], v[12:15]
	s_nop 7
	v_cvt_pk_bf16_f32 v12, v12, v13
	v_cvt_pk_bf16_f32 v13, v14, v15
	v_lshl_add_u64 v[14:15], v[28:29], 0, v[2:3]
	global_store_dwordx2 v[14:15], v[12:13], off
	ds_read_b64_tr_b16 v[12:13], v4 offset:9312
	ds_read_b64_tr_b16 v[14:15], v4 offset:9888
	ds_read_b64_tr_b16 v[16:17], v0 offset:13920
	ds_read_b64_tr_b16 v[18:19], v0 offset:14496
	ds_read_b64_tr_b16 v[20:21], v4
	ds_read_b64_tr_b16 v[22:23], v4 offset:576
	ds_read_b64_tr_b16 v[24:25], v0 offset:4608
	ds_read_b64_tr_b16 v[26:27], v0 offset:5184
	s_waitcnt lgkmcnt(0)
	v_mfma_f32_16x16x32_bf16 v[20:23], v[12:15], v[20:23], 0
	v_lshl_add_u64 v[28:29], v[6:7], 0, s[20:21]
	v_mfma_f32_16x16x32_bf16 v[20:23], v[16:19], v[24:27], v[20:23]
	s_nop 7
	v_cvt_pk_bf16_f32 v6, v20, v21
	v_cvt_pk_bf16_f32 v7, v22, v23
	global_store_dwordx2 v[8:9], v[6:7], off offset:96
	ds_read_b64_tr_b16 v[20:21], v4 offset:32
	ds_read_b64_tr_b16 v[22:23], v4 offset:608
	ds_read_b64_tr_b16 v[24:25], v0 offset:4640
	ds_read_b64_tr_b16 v[26:27], v0 offset:5216
	s_waitcnt lgkmcnt(0)
	v_mfma_f32_16x16x32_bf16 v[20:23], v[12:15], v[20:23], 0
	v_mfma_f32_16x16x32_bf16 v[20:23], v[16:19], v[24:27], v[20:23]
	s_nop 7
	v_cvt_pk_bf16_f32 v6, v20, v21
	v_cvt_pk_bf16_f32 v7, v22, v23
	global_store_dwordx2 v[8:9], v[6:7], off offset:2144
	ds_read_b64_tr_b16 v[6:7], v4 offset:64
	ds_read_b64_tr_b16 v[8:9], v4 offset:640
	ds_read_b64_tr_b16 v[20:21], v0 offset:4672
	ds_read_b64_tr_b16 v[22:23], v0 offset:5248
	s_waitcnt lgkmcnt(0)
	v_mfma_f32_16x16x32_bf16 v[6:9], v[12:15], v[6:9], 0
	v_mfma_f32_16x16x32_bf16 v[6:9], v[16:19], v[20:23], v[6:9]
	s_nop 7
	v_cvt_pk_bf16_f32 v6, v6, v7
	v_cvt_pk_bf16_f32 v7, v8, v9
	v_lshl_add_u64 v[8:9], v[28:29], 0, v[10:11]
	global_store_dwordx2 v[8:9], v[6:7], off
	ds_read_b64_tr_b16 v[6:7], v4 offset:96
	ds_read_b64_tr_b16 v[8:9], v4 offset:672
	s_waitcnt lgkmcnt(0)
	v_mfma_f32_16x16x32_bf16 v[4:7], v[12:15], v[6:9], 0
	ds_read_b64_tr_b16 v[8:9], v0 offset:4704
	ds_read_b64_tr_b16 v[10:11], v0 offset:5280
	s_waitcnt lgkmcnt(0)
	v_mfma_f32_16x16x32_bf16 v[4:7], v[16:19], v[8:11], v[4:7]
	s_nop 7
	v_cvt_pk_bf16_f32 v0, v4, v5
	v_cvt_pk_bf16_f32 v1, v6, v7
	v_lshl_add_u64 v[4:5], v[28:29], 0, v[2:3]
	global_store_dwordx2 v[4:5], v[0:1], off
	s_waitcnt lgkmcnt(0)

; __device__ __forceinline__ float row_sum_incl(float v) { v += dpp_shr0<1>(v); v += dpp_shr0<2>(v); v += dpp_shr0<4>(v); v += dpp_shr0<8>(v); return v; }
; __device__ __forceinline__ float bcast15(float v, int lane) { return bperm_f((lane & 48) | 15, v); }
; __device__ __forceinline__ void w_hg_scan(const float (&lbv)[8], const bf16_t* fsrc, int lane, float (&bb)[4][8], float (&r31)[8], float (&r63)[8]) {
;     ...
;     float carry[8];
; #pragma unroll
;     for (int j = 0; j < 8; ++j) carry[j] = 0.f;
; #pragma unroll
;     for (int tb = 0; tb < 4; ++tb) {
; #pragma unroll
;         for (int j = 0; j < 8; ++j) { const float v = row_sum_incl(bb[tb][j]) + carry[j]; bb[tb][j] = v; carry[j] = bcast15(v, lane); if (tb == 1) r31[j] = carry[j]; if (tb == 3) r63[j] = carry[j]; }
;         __builtin_amdgcn_sched_barrier(0);
;     }
; }
; __device__ __forceinline__ void w_hg_m1(const Args& a, int l, unsigned char* ws, const bf16_t* proj, LAS unsigned char* wl, int b, int ck_, int h, int lane) {
;     ...
;         if (lo == 0) { float* dp = (float*)(ws + WS_HGDEC) + (size_t)((b * NCH + ck_) * 4 + h) * 64 + 32 * kk + 8 * fq;
.LBB0_669:
	s_or_b64 exec, exec, s[34:35]
	v_add_f32_dpp v28, v28, v28 row_shr:1 row_mask:0xf bank_mask:0xf bound_ctrl:1
	s_lshl_b32 s21, s21, 9
	s_lshl_b32 s27, s27, 2
	v_add_f32_dpp v28, v28, v28 row_shr:2 row_mask:0xf bank_mask:0xf bound_ctrl:1
	s_add_i32 s21, s27, s21
	s_add_i32 s62, s21, s20
	v_add_f32_dpp v28, v28, v28 row_shr:4 row_mask:0xf bank_mask:0xf bound_ctrl:1
	s_ashr_i32 s63, s62, 31
	s_lshl_b64 s[20:21], s[62:63], 8
	v_add_f32_dpp v28, v28, v28 row_shr:8 row_mask:0xf bank_mask:0xf bound_ctrl:1
	v_add_f32_e32 v74, 0, v28
	s_add_u32 s20, s14, s20
	v_add_f32_dpp v28, v29, v29 row_shr:1 row_mask:0xf bank_mask:0xf bound_ctrl:1
	s_addc_u32 s21, s15, s21
	v_lshl_add_u64 v[8:9], v[0:1], 2, s[20:21]
	v_add_f32_dpp v28, v28, v28 row_shr:2 row_mask:0xf bank_mask:0xf bound_ctrl:1
	v_add_f32_dpp v1, v24, v24 row_shr:1 row_mask:0xf bank_mask:0xf bound_ctrl:1
	v_add_f32_dpp v25, v25, v25 row_shr:1 row_mask:0xf bank_mask:0xf bound_ctrl:1
	v_add_f32_dpp v28, v28, v28 row_shr:4 row_mask:0xf bank_mask:0xf bound_ctrl:1
	v_add_f32_dpp v29, v35, v35 row_shr:1 row_mask:0xf bank_mask:0xf bound_ctrl:1
	v_add_f32_dpp v1, v1, v1 row_shr:2 row_mask:0xf bank_mask:0xf bound_ctrl:1
	v_add_f32_dpp v28, v28, v28 row_shr:8 row_mask:0xf bank_mask:0xf bound_ctrl:1
	v_add_f32_e32 v75, 0, v28
	v_add_f32_dpp v25, v25, v25 row_shr:2 row_mask:0xf bank_mask:0xf bound_ctrl:1
	v_add_f32_dpp v28, v31, v31 row_shr:1 row_mask:0xf bank_mask:0xf bound_ctrl:1
	v_add_f32_dpp v29, v29, v29 row_shr:2 row_mask:0xf bank_mask:0xf bound_ctrl:1
	v_add_f32_dpp v1, v1, v1 row_shr:4 row_mask:0xf bank_mask:0xf bound_ctrl:1
	v_add_f32_dpp v28, v28, v28 row_shr:2 row_mask:0xf bank_mask:0xf bound_ctrl:1
	v_add_f32_dpp v25, v25, v25 row_shr:4 row_mask:0xf bank_mask:0xf bound_ctrl:1
	v_add_f32_dpp v29, v29, v29 row_shr:4 row_mask:0xf bank_mask:0xf bound_ctrl:1
	v_add_f32_dpp v28, v28, v28 row_shr:4 row_mask:0xf bank_mask:0xf bound_ctrl:1
	v_lshlrev_b32_e32 v2, 2, v33
	v_add_f32_dpp v1, v1, v1 row_shr:8 row_mask:0xf bank_mask:0xf bound_ctrl:1
	v_add_f32_dpp v25, v25, v25 row_shr:8 row_mask:0xf bank_mask:0xf bound_ctrl:1
	v_add_f32_dpp v28, v28, v28 row_shr:8 row_mask:0xf bank_mask:0xf bound_ctrl:1
	v_add_f32_dpp v29, v29, v29 row_shr:8 row_mask:0xf bank_mask:0xf bound_ctrl:1
	v_and_b32_e32 v30, 0xc0, v2
	v_add_f32_e32 v24, 0, v1
	v_add_f32_e32 v25, 0, v25
	v_add_f32_e32 v28, 0, v28
	v_add_f32_e32 v29, 0, v29
	ds_bpermute_b32 v1, v30, v24 offset:60
	ds_bpermute_b32 v38, v30, v25 offset:60
	v_add_f32_dpp v26, v26, v26 row_shr:1 row_mask:0xf bank_mask:0xf bound_ctrl:1
	v_add_f32_dpp v27, v27, v27 row_shr:1 row_mask:0xf bank_mask:0xf bound_ctrl:1
	ds_bpermute_b32 v40, v30, v74 offset:60
	ds_bpermute_b32 v31, v30, v28 offset:60
	ds_bpermute_b32 v35, v30, v29 offset:60
	v_add_f32_dpp v26, v26, v26 row_shr:2 row_mask:0xf bank_mask:0xf bound_ctrl:1
	v_add_f32_dpp v27, v27, v27 row_shr:2 row_mask:0xf bank_mask:0xf bound_ctrl:1
	s_mov_b64 s[34:35], 0x18000
	v_add_f32_dpp v26, v26, v26 row_shr:4 row_mask:0xf bank_mask:0xf bound_ctrl:1
	v_add_f32_dpp v27, v27, v27 row_shr:4 row_mask:0xf bank_mask:0xf bound_ctrl:1
	v_lshl_add_u64 v[10:11], v[14:15], 0, s[34:35]
	v_add_f32_dpp v26, v26, v26 row_shr:8 row_mask:0xf bank_mask:0xf bound_ctrl:1
	v_add_f32_dpp v27, v27, v27 row_shr:8 row_mask:0xf bank_mask:0xf bound_ctrl:1
	v_lshl_add_u32 v2, v0, 1, s6
	v_cmp_eq_u32_e64 s[38:39], 0, v34
	v_add_f32_e32 v72, 0, v26
	v_add_f32_e32 v73, 0, v27
	ds_bpermute_b32 v26, v30, v72 offset:60
	ds_bpermute_b32 v27, v30, v73 offset:60
	ds_bpermute_b32 v53, v30, v75 offset:60
	v_add_f32_dpp v36, v36, v36 row_shr:1 row_mask:0xf bank_mask:0xf bound_ctrl:1
	s_nop 1
	v_add_f32_dpp v36, v36, v36 row_shr:2 row_mask:0xf bank_mask:0xf bound_ctrl:1
	s_nop 1
	v_add_f32_dpp v36, v36, v36 row_shr:4 row_mask:0xf bank_mask:0xf bound_ctrl:1
	s_nop 1
	v_add_f32_dpp v36, v36, v36 row_shr:8 row_mask:0xf bank_mask:0xf bound_ctrl:1
	s_waitcnt lgkmcnt(7)
	v_add_f32_e32 v68, v36, v1
	ds_bpermute_b32 v1, v30, v68 offset:60
	v_add_f32_dpp v36, v41, v41 row_shr:1 row_mask:0xf bank_mask:0xf bound_ctrl:1
	v_add_f32_dpp v41, v46, v46 row_shr:1 row_mask:0xf bank_mask:0xf bound_ctrl:1
	s_nop 0
	v_add_f32_dpp v36, v36, v36 row_shr:2 row_mask:0xf bank_mask:0xf bound_ctrl:1
	v_add_f32_dpp v41, v41, v41 row_shr:2 row_mask:0xf bank_mask:0xf bound_ctrl:1
	s_nop 0
	v_add_f32_dpp v36, v36, v36 row_shr:4 row_mask:0xf bank_mask:0xf bound_ctrl:1
	v_add_f32_dpp v41, v41, v41 row_shr:4 row_mask:0xf bank_mask:0xf bound_ctrl:1
	s_nop 0
	v_add_f32_dpp v36, v36, v36 row_shr:8 row_mask:0xf bank_mask:0xf bound_ctrl:1
	s_waitcnt lgkmcnt(7)
	v_add_f32_e32 v67, v36, v38
	v_add_f32_dpp v38, v42, v42 row_shr:1 row_mask:0xf bank_mask:0xf bound_ctrl:1
	v_add_f32_dpp v41, v41, v41 row_shr:8 row_mask:0xf bank_mask:0xf bound_ctrl:1
	s_waitcnt lgkmcnt(5)
	v_add_f32_e32 v59, v41, v31
	v_add_f32_dpp v38, v38, v38 row_shr:2 row_mask:0xf bank_mask:0xf bound_ctrl:1
	v_add_f32_dpp v41, v47, v47 row_shr:1 row_mask:0xf bank_mask:0xf bound_ctrl:1
	ds_bpermute_b32 v36, v30, v67 offset:60
	v_add_f32_dpp v38, v38, v38 row_shr:4 row_mask:0xf bank_mask:0xf bound_ctrl:1
	v_add_f32_dpp v41, v41, v41 row_shr:2 row_mask:0xf bank_mask:0xf bound_ctrl:1
	ds_bpermute_b32 v31, v30, v59 offset:60
	v_add_f32_dpp v38, v38, v38 row_shr:8 row_mask:0xf bank_mask:0xf bound_ctrl:1
	s_waitcnt lgkmcnt(5)
; __device__ __forceinline__ float row_sum_incl(float v) { v += dpp_shr0<1>(v); v += dpp_shr0<2>(v); v += dpp_shr0<4>(v); v += dpp_shr0<8>(v); return v; }
; __device__ __forceinline__ float bcast15(float v, int lane) { return bperm_f((lane & 48) | 15, v); }
; __device__ __forceinline__ void w_hg_scan(const float (&lbv)[8], const bf16_t* fsrc, int lane, float (&bb)[4][8], float (&r31)[8], float (&r63)[8]) {
;     ...
;     for (int tb = 0; tb < 4; ++tb) {
; #pragma unroll
;         for (int j = 0; j < 8; ++j) { const float v = row_sum_incl(bb[tb][j]) + carry[j]; bb[tb][j] = v; carry[j] = bcast15(v, lane); if (tb == 1) r31[j] = carry[j]; if (tb == 3) r63[j] = carry[j]; }
;         __builtin_amdgcn_sched_barrier(0);
;     }
	v_add_f32_e32 v65, v38, v26
	v_add_f32_dpp v41, v41, v41 row_shr:4 row_mask:0xf bank_mask:0xf bound_ctrl:1
	v_add_f32_dpp v38, v43, v43 row_shr:1 row_mask:0xf bank_mask:0xf bound_ctrl:1
	ds_bpermute_b32 v26, v30, v65 offset:60
	v_add_f32_dpp v41, v41, v41 row_shr:8 row_mask:0xf bank_mask:0xf bound_ctrl:1
	v_add_f32_dpp v38, v38, v38 row_shr:2 row_mask:0xf bank_mask:0xf bound_ctrl:1
	v_add_f32_e32 v58, v41, v35
	ds_bpermute_b32 v35, v30, v58 offset:60
	v_add_f32_dpp v38, v38, v38 row_shr:4 row_mask:0xf bank_mask:0xf bound_ctrl:1
	s_nop 1
	v_add_f32_dpp v38, v38, v38 row_shr:8 row_mask:0xf bank_mask:0xf bound_ctrl:1
	s_waitcnt lgkmcnt(6)
	v_add_f32_e32 v64, v38, v27
	ds_bpermute_b32 v27, v30, v64 offset:60
	v_add_f32_dpp v38, v44, v44 row_shr:1 row_mask:0xf bank_mask:0xf bound_ctrl:1
	s_nop 1
	v_add_f32_dpp v38, v38, v38 row_shr:2 row_mask:0xf bank_mask:0xf bound_ctrl:1
	s_nop 1
	v_add_f32_dpp v38, v38, v38 row_shr:4 row_mask:0xf bank_mask:0xf bound_ctrl:1
	s_nop 1
	v_add_f32_dpp v38, v38, v38 row_shr:8 row_mask:0xf bank_mask:0xf bound_ctrl:1
	v_add_f32_e32 v62, v38, v40
	v_add_f32_dpp v40, v45, v45 row_shr:1 row_mask:0xf bank_mask:0xf bound_ctrl:1
	ds_bpermute_b32 v38, v30, v62 offset:60
	s_nop 0
	v_add_f32_dpp v40, v40, v40 row_shr:2 row_mask:0xf bank_mask:0xf bound_ctrl:1
	s_nop 1
	v_add_f32_dpp v40, v40, v40 row_shr:4 row_mask:0xf bank_mask:0xf bound_ctrl:1
	s_nop 1
	v_add_f32_dpp v40, v40, v40 row_shr:8 row_mask:0xf bank_mask:0xf bound_ctrl:1
	s_waitcnt lgkmcnt(7)
	v_add_f32_e32 v61, v40, v53
	ds_bpermute_b32 v40, v30, v61 offset:60
	v_add_f32_dpp v41, v48, v48 row_shr:1 row_mask:0xf bank_mask:0xf bound_ctrl:1
	s_nop 1
	v_add_f32_dpp v41, v41, v41 row_shr:2 row_mask:0xf bank_mask:0xf bound_ctrl:1
	s_nop 1
	v_add_f32_dpp v41, v41, v41 row_shr:4 row_mask:0xf bank_mask:0xf bound_ctrl:1
	s_nop 1
	v_add_f32_dpp v41, v41, v41 row_shr:8 row_mask:0xf bank_mask:0xf bound_ctrl:1
	s_waitcnt lgkmcnt(7)
	v_add_f32_e32 v57, v41, v1
	ds_bpermute_b32 v1, v30, v57 offset:60
	v_add_f32_dpp v41, v49, v49 row_shr:1 row_mask:0xf bank_mask:0xf bound_ctrl:1
	s_nop 1
	v_add_f32_dpp v41, v41, v41 row_shr:2 row_mask:0xf bank_mask:0xf bound_ctrl:1
	s_nop 1
	v_add_f32_dpp v41, v41, v41 row_shr:4 row_mask:0xf bank_mask:0xf bound_ctrl:1
	s_nop 1
	v_add_f32_dpp v41, v41, v41 row_shr:8 row_mask:0xf bank_mask:0xf bound_ctrl:1
	s_waitcnt lgkmcnt(7)
	v_add_f32_e32 v56, v41, v36
	ds_bpermute_b32 v36, v30, v56 offset:60
	v_add_f32_dpp v41, v50, v50 row_shr:1 row_mask:0xf bank_mask:0xf bound_ctrl:1
	s_nop 1
	v_add_f32_dpp v41, v41, v41 row_shr:2 row_mask:0xf bank_mask:0xf bound_ctrl:1
	s_nop 1
	v_add_f32_dpp v41, v41, v41 row_shr:4 row_mask:0xf bank_mask:0xf bound_ctrl:1
	s_nop 1
	v_add_f32_dpp v41, v41, v41 row_shr:8 row_mask:0xf bank_mask:0xf bound_ctrl:1
	s_waitcnt lgkmcnt(6)
	v_add_f32_e32 v55, v41, v26
	ds_bpermute_b32 v26, v30, v55 offset:60
	v_add_f32_dpp v41, v51, v51 row_shr:1 row_mask:0xf bank_mask:0xf bound_ctrl:1
	s_nop 1
	v_add_f32_dpp v41, v41, v41 row_shr:2 row_mask:0xf bank_mask:0xf bound_ctrl:1
	s_nop 1
	v_add_f32_dpp v41, v41, v41 row_shr:4 row_mask:0xf bank_mask:0xf bound_ctrl:1
	s_nop 1
	v_add_f32_dpp v41, v41, v41 row_shr:8 row_mask:0xf bank_mask:0xf bound_ctrl:1
	s_waitcnt lgkmcnt(5)
	v_add_f32_e32 v54, v41, v27
	ds_bpermute_b32 v27, v30, v54 offset:60
	v_add_f32_dpp v41, v52, v52 row_shr:1 row_mask:0xf bank_mask:0xf bound_ctrl:1
	s_nop 1
	v_add_f32_dpp v41, v41, v41 row_shr:2 row_mask:0xf bank_mask:0xf bound_ctrl:1
	s_nop 1
	v_add_f32_dpp v41, v41, v41 row_shr:4 row_mask:0xf bank_mask:0xf bound_ctrl:1
	s_nop 1
	v_add_f32_dpp v41, v41, v41 row_shr:8 row_mask:0xf bank_mask:0xf bound_ctrl:1
	s_waitcnt lgkmcnt(5)
	v_add_f32_e32 v53, v41, v38
	v_add_f32_dpp v38, v60, v60 row_shr:1 row_mask:0xf bank_mask:0xf bound_ctrl:1
	ds_bpermute_b32 v41, v30, v53 offset:60
	s_nop 0
	v_add_f32_dpp v38, v38, v38 row_shr:2 row_mask:0xf bank_mask:0xf bound_ctrl:1
	s_nop 1
	v_add_f32_dpp v38, v38, v38 row_shr:4 row_mask:0xf bank_mask:0xf bound_ctrl:1
	s_nop 1
	v_add_f32_dpp v38, v38, v38 row_shr:8 row_mask:0xf bank_mask:0xf bound_ctrl:1
	s_waitcnt lgkmcnt(5)
	v_add_f32_e32 v52, v38, v40
	ds_bpermute_b32 v40, v30, v52 offset:60
	v_add_f32_dpp v38, v63, v63 row_shr:1 row_mask:0xf bank_mask:0xf bound_ctrl:1
	s_nop 1
	v_add_f32_dpp v38, v38, v38 row_shr:2 row_mask:0xf bank_mask:0xf bound_ctrl:1
	s_nop 1
	v_add_f32_dpp v38, v38, v38 row_shr:4 row_mask:0xf bank_mask:0xf bound_ctrl:1
	s_nop 1
	v_add_f32_dpp v38, v38, v38 row_shr:8 row_mask:0xf bank_mask:0xf bound_ctrl:1
	v_add_f32_e32 v51, v38, v31
	v_add_f32_dpp v31, v66, v66 row_shr:1 row_mask:0xf bank_mask:0xf bound_ctrl:1
	ds_bpermute_b32 v42, v30, v51 offset:60
	s_nop 0
	v_add_f32_dpp v31, v31, v31 row_shr:2 row_mask:0xf bank_mask:0xf bound_ctrl:1
	s_nop 1
	v_add_f32_dpp v31, v31, v31 row_shr:4 row_mask:0xf bank_mask:0xf bound_ctrl:1
	s_nop 1
	v_add_f32_dpp v31, v31, v31 row_shr:8 row_mask:0xf bank_mask:0xf bound_ctrl:1
	v_add_f32_e32 v50, v31, v35
	ds_bpermute_b32 v49, v30, v50 offset:60
	v_add_f32_dpp v4, v4, v4 row_shr:1 row_mask:0xf bank_mask:0xf bound_ctrl:1
	v_add_f32_dpp v31, v69, v69 row_shr:1 row_mask:0xf bank_mask:0xf bound_ctrl:1
	s_nop 0
	v_add_f32_dpp v4, v4, v4 row_shr:2 row_mask:0xf bank_mask:0xf bound_ctrl:1
	v_add_f32_dpp v31, v31, v31 row_shr:2 row_mask:0xf bank_mask:0xf bound_ctrl:1
	s_nop 0
	v_add_f32_dpp v4, v4, v4 row_shr:4 row_mask:0xf bank_mask:0xf bound_ctrl:1
	v_add_f32_dpp v31, v31, v31 row_shr:4 row_mask:0xf bank_mask:0xf bound_ctrl:1
	s_nop 0
	v_add_f32_dpp v4, v4, v4 row_shr:8 row_mask:0xf bank_mask:0xf bound_ctrl:1
	s_waitcnt lgkmcnt(6)
; #define LAS __attribute__((address_space(3)))
; __device__ __forceinline__ u32x4 pack8(const float (&v)[8]) { u32x4 w; w.x = pk2(v[0], v[1]); w.y = pk2(v[2], v[3]); w.z = pk2(v[4], v[5]); w.w = pk2(v[6], v[7]); return w; }
; __device__ __forceinline__ void ld8bf(const bf16_t* p, float (&o)[8]) { unpack8(*(const u32x4*)p, o); }
; __device__ __forceinline__ float row_sum_incl(float v) { v += dpp_shr0<1>(v); v += dpp_shr0<2>(v); v += dpp_shr0<4>(v); v += dpp_shr0<8>(v); return v; }
; __device__ __forceinline__ float bcast15(float v, int lane) { return bperm_f((lane & 48) | 15, v); }
; __device__ __forceinline__ void w_hg_scan(const float (&lbv)[8], const bf16_t* fsrc, int lane, float (&bb)[4][8], float (&r31)[8], float (&r63)[8]) {
;     ...
;     for (int tb = 0; tb < 4; ++tb) {
; #pragma unroll
;         for (int j = 0; j < 8; ++j) { const float v = row_sum_incl(bb[tb][j]) + carry[j]; bb[tb][j] = v; carry[j] = bcast15(v, lane); if (tb == 1) r31[j] = carry[j]; if (tb == 3) r63[j] = carry[j]; }
;         __builtin_amdgcn_sched_barrier(0);
;     }
; __device__ __forceinline__ void w_hg_m1(const Args& a, int l, unsigned char* ws, const bf16_t* proj, LAS unsigned char* wl, int b, int ck_, int h, int lane) {
;     ...
; #pragma unroll
;         for (int tb = 0; tb < 4; ++tb) { float fp[8]; ld8bf(fsrc + (size_t)(16 * tb + lo) * NIN, fp);
;             float kb[8];
; #pragma unroll
;             for (int j = 0; j < 8; ++j) { float lf, key; hg_lf_key(fp[j], lbv[j], lf, key); kb[j] = key * __expf(r63[j] - bb[tb][j]); }
;             *(LAS u32x4*)(kT + (16 * tb + lo) * LD + 32 * kk + 8 * fq) = pack8(kb); }
	v_add_f32_e32 v47, v4, v36
	v_add_f32_dpp v31, v31, v31 row_shr:8 row_mask:0xf bank_mask:0xf bound_ctrl:1
	v_add_f32_dpp v4, v70, v70 row_shr:1 row_mask:0xf bank_mask:0xf bound_ctrl:1
	v_add_f32_e32 v48, v31, v1
	ds_bpermute_b32 v1, v30, v48 offset:60
	v_add_f32_dpp v4, v4, v4 row_shr:2 row_mask:0xf bank_mask:0xf bound_ctrl:1
	ds_bpermute_b32 v31, v30, v47 offset:60
	s_nop 0
	v_add_f32_dpp v4, v4, v4 row_shr:4 row_mask:0xf bank_mask:0xf bound_ctrl:1
	s_nop 1
	v_add_f32_dpp v4, v4, v4 row_shr:8 row_mask:0xf bank_mask:0xf bound_ctrl:1
	s_waitcnt lgkmcnt(7)
	v_add_f32_e32 v46, v4, v26
	ds_bpermute_b32 v36, v30, v46 offset:60
	v_add_f32_dpp v4, v5, v5 row_shr:1 row_mask:0xf bank_mask:0xf bound_ctrl:1
	s_nop 1
	v_add_f32_dpp v4, v4, v4 row_shr:2 row_mask:0xf bank_mask:0xf bound_ctrl:1
	s_nop 1
	v_add_f32_dpp v4, v4, v4 row_shr:4 row_mask:0xf bank_mask:0xf bound_ctrl:1
	s_nop 1
	v_add_f32_dpp v4, v4, v4 row_shr:8 row_mask:0xf bank_mask:0xf bound_ctrl:1
	s_waitcnt lgkmcnt(7)
	v_add_f32_e32 v45, v4, v27
	ds_bpermute_b32 v38, v30, v45 offset:60
	v_add_f32_dpp v4, v37, v37 row_shr:1 row_mask:0xf bank_mask:0xf bound_ctrl:1
	s_nop 1
	v_add_f32_dpp v4, v4, v4 row_shr:2 row_mask:0xf bank_mask:0xf bound_ctrl:1
	s_nop 1
	v_add_f32_dpp v4, v4, v4 row_shr:4 row_mask:0xf bank_mask:0xf bound_ctrl:1
	s_nop 1
	v_add_f32_dpp v4, v4, v4 row_shr:8 row_mask:0xf bank_mask:0xf bound_ctrl:1
	s_waitcnt lgkmcnt(7)
	v_add_f32_e32 v44, v4, v41
	ds_bpermute_b32 v35, v30, v44 offset:60
	v_add_f32_dpp v4, v6, v6 row_shr:1 row_mask:0xf bank_mask:0xf bound_ctrl:1
	s_nop 1
	v_add_f32_dpp v4, v4, v4 row_shr:2 row_mask:0xf bank_mask:0xf bound_ctrl:1
	s_nop 1
	v_add_f32_dpp v4, v4, v4 row_shr:4 row_mask:0xf bank_mask:0xf bound_ctrl:1
	s_nop 1
	v_add_f32_dpp v4, v4, v4 row_shr:8 row_mask:0xf bank_mask:0xf bound_ctrl:1
	s_waitcnt lgkmcnt(7)
	v_add_f32_e32 v43, v4, v40
	ds_bpermute_b32 v37, v30, v43 offset:60
	v_add_f32_dpp v4, v39, v39 row_shr:1 row_mask:0xf bank_mask:0xf bound_ctrl:1
	s_nop 1
	v_add_f32_dpp v4, v4, v4 row_shr:2 row_mask:0xf bank_mask:0xf bound_ctrl:1
	s_nop 1
	v_add_f32_dpp v4, v4, v4 row_shr:4 row_mask:0xf bank_mask:0xf bound_ctrl:1
	s_nop 1
	v_add_f32_dpp v4, v4, v4 row_shr:8 row_mask:0xf bank_mask:0xf bound_ctrl:1
	s_waitcnt lgkmcnt(7)
	v_add_f32_e32 v42, v4, v42
	ds_bpermute_b32 v39, v30, v42 offset:60
	v_add_f32_dpp v4, v7, v7 row_shr:1 row_mask:0xf bank_mask:0xf bound_ctrl:1
	s_nop 1
	v_add_f32_dpp v4, v4, v4 row_shr:2 row_mask:0xf bank_mask:0xf bound_ctrl:1
	s_nop 1
	v_add_f32_dpp v4, v4, v4 row_shr:4 row_mask:0xf bank_mask:0xf bound_ctrl:1
	s_nop 1
	v_add_f32_dpp v4, v4, v4 row_shr:8 row_mask:0xf bank_mask:0xf bound_ctrl:1
	s_waitcnt lgkmcnt(7)
	v_add_f32_e32 v41, v4, v49
	ds_bpermute_b32 v40, v30, v41 offset:60
	v_mov_b64_e32 v[4:5], v[222:223]
	v_mov_b64_e32 v[6:7], v[224:225]
	s_waitcnt lgkmcnt(0)
	v_sub_f32_e32 v24, v1, v24
	v_sub_f32_e32 v25, v31, v25
	v_mul_f32_e32 v24, 0x3fb8aa3b, v24
	v_mul_f32_e32 v25, 0x3fb8aa3b, v25
	v_exp_f32_e32 v24, v24
	v_exp_f32_e32 v25, v25
	v_pk_add_f32 v[22:23], v[22:23], 1.0 op_sel_hi:[1,0] neg_lo:[1,0] neg_hi:[1,0]
	v_pk_add_f32 v[20:21], v[20:21], 1.0 op_sel_hi:[1,0] neg_lo:[1,0] neg_hi:[1,0]
	v_pk_add_f32 v[18:19], v[18:19], 1.0 op_sel_hi:[1,0] neg_lo:[1,0] neg_hi:[1,0]
	s_waitcnt vmcnt(0)
	v_lshlrev_b32_e32 v49, 16, v4
	v_mul_f32_e64 v26, |v49|, s26
	v_exp_f32_e32 v26, v26
	v_and_b32_e32 v4, 0xffff0000, v4
	v_cmp_le_f32_e32 vcc, 0, v49
	v_cmp_le_f32_e64 s[42:43], 0, v4
	v_add_f32_e32 v27, 1.0, v26
	v_rcp_f32_e32 v70, v27
	v_mul_f32_e64 v27, |v4|, s26
	v_exp_f32_e32 v27, v27
	v_sub_f32_e32 v4, v36, v72
	v_mul_f32_e32 v4, 0x3fb8aa3b, v4
	v_lshlrev_b32_e32 v49, 16, v5
	v_add_f32_e32 v60, 1.0, v27
	v_rcp_f32_e32 v71, v60
	v_and_b32_e32 v60, 0xffff0000, v5
	v_pk_mul_f32 v[26:27], v[26:27], v[70:71]
	s_nop 0
	v_cndmask_b32_e64 v27, v71, v27, s[42:43]
	v_cndmask_b32_e32 v26, v70, v26, vcc
	v_pk_mul_f32 v[26:27], v[22:23], v[26:27]
	v_cmp_le_f32_e32 vcc, 0, v49
	v_pk_mul_f32 v[24:25], v[24:25], v[26:27]
	v_exp_f32_e32 v26, v4
	v_sub_f32_e32 v4, v38, v73
	v_mul_f32_e32 v4, 0x3fb8aa3b, v4
	v_exp_f32_e32 v27, v4
	v_mul_f32_e64 v4, |v49|, s26
	v_exp_f32_e32 v4, v4
	v_lshlrev_b32_e32 v49, 16, v6
	v_cmp_le_f32_e64 s[42:43], 0, v60
	v_and_b32_e32 v6, 0xffff0000, v6
	v_add_f32_e32 v5, 1.0, v4
	v_rcp_f32_e32 v70, v5
	v_mul_f32_e64 v5, |v60|, s26
	v_exp_f32_e32 v5, v5
	v_mul_f32_e64 v60, |v49|, s26
	v_cvt_pk_bf16_f32 v24, v24, v25
	v_add_f32_e32 v63, 1.0, v5
	v_rcp_f32_e32 v71, v63
	s_nop 0
	v_pk_mul_f32 v[4:5], v[4:5], v[70:71]
	s_nop 0
	v_cndmask_b32_e32 v4, v70, v4, vcc
	v_exp_f32_e32 v70, v60
	v_cndmask_b32_e64 v5, v71, v5, s[42:43]
	v_cmp_le_f32_e64 s[42:43], 0, v6
	v_pk_mul_f32 v[4:5], v[20:21], v[4:5]
	v_add_f32_e32 v60, 1.0, v70
	v_rcp_f32_e32 v72, v60
	v_mul_f32_e64 v60, |v6|, s26
	v_exp_f32_e32 v71, v60
	v_sub_f32_e32 v6, v39, v28
	v_mul_f32_e32 v6, 0x3fb8aa3b, v6
	v_exp_f32_e32 v28, v6
	v_add_f32_e32 v60, 1.0, v71
	v_sub_f32_e32 v6, v40, v29
	v_rcp_f32_e32 v73, v60
	v_cmp_le_f32_e32 vcc, 0, v49
	v_mul_f32_e32 v6, 0x3fb8aa3b, v6
	v_lshlrev_b32_e32 v49, 16, v7
	v_pk_mul_f32 v[4:5], v[26:27], v[4:5]
	v_sub_f32_e32 v26, v35, v74
	v_sub_f32_e32 v27, v37, v75
	v_exp_f32_e32 v29, v6
	v_mul_f32_e64 v6, |v49|, s26
	v_mul_f32_e32 v26, 0x3fb8aa3b, v26
	v_mul_f32_e32 v27, 0x3fb8aa3b, v27
	v_exp_f32_e32 v6, v6
	v_exp_f32_e32 v26, v26
	v_exp_f32_e32 v27, v27
	v_pk_mul_f32 v[70:71], v[70:71], v[72:73]
	v_and_b32_e32 v60, 0xffff0000, v7
	v_cndmask_b32_e64 v71, v73, v71, s[42:43]
	v_cndmask_b32_e32 v70, v72, v70, vcc
	v_pk_mul_f32 v[70:71], v[18:19], v[70:71]
	v_add_f32_e32 v7, 1.0, v6
	v_pk_mul_f32 v[26:27], v[26:27], v[70:71]
	v_rcp_f32_e32 v70, v7
	v_mul_f32_e64 v7, |v60|, s26
	v_exp_f32_e32 v7, v7
	v_cmp_le_f32_e32 vcc, 0, v49
	v_cmp_le_f32_e64 s[42:43], 0, v60
	v_cvt_pk_bf16_f32 v25, v4, v5
	v_add_f32_e32 v63, 1.0, v7
	v_rcp_f32_e32 v71, v63
	v_cvt_pk_bf16_f32 v26, v26, v27
	v_mad_u32_u24 v49, v34, s23, v2
	v_pk_mul_f32 v[6:7], v[6:7], v[70:71]
	s_nop 0
	v_cndmask_b32_e64 v7, v71, v7, s[42:43]
	v_cndmask_b32_e32 v6, v70, v6, vcc
	v_pk_mul_f32 v[6:7], v[16:17], v[6:7]
	s_nop 0
	v_pk_mul_f32 v[6:7], v[28:29], v[6:7]
	s_nop 0
	v_cvt_pk_bf16_f32 v27, v6, v7
	ds_write_b128 v49, v[24:27] offset:9216
	v_mov_b64_e32 v[4:5], v[226:227]
	v_mov_b64_e32 v[6:7], v[228:229]
	v_sub_f32_e32 v24, v1, v68
	v_sub_f32_e32 v25, v31, v67
	v_mul_f32_e32 v24, 0x3fb8aa3b, v24
	v_mul_f32_e32 v25, 0x3fb8aa3b, v25
	v_exp_f32_e32 v24, v24
	v_exp_f32_e32 v25, v25
	s_waitcnt vmcnt(0) lgkmcnt(0)
; #define LAS __attribute__((address_space(3)))
; __device__ __forceinline__ u32x4 pack8(const float (&v)[8]) { u32x4 w; w.x = pk2(v[0], v[1]); w.y = pk2(v[2], v[3]); w.z = pk2(v[4], v[5]); w.w = pk2(v[6], v[7]); return w; }
; __device__ __forceinline__ void ld8bf(const bf16_t* p, float (&o)[8]) { unpack8(*(const u32x4*)p, o); }
; __device__ __forceinline__ void hg_lf_key(float fp, float lb, float& lf, float& key) {
;     const float e = __expf(-fabsf(fp));
;     const float rc = __builtin_amdgcn_rcpf(1.0f + e);
;     const float sp = fp >= 0.f ? rc : e * rc;
;     const float sn = fp >= 0.f ? e * rc : rc;
;     const float lsig = (fp >= 0.f ? 0.f : fp) + __logf(rc);
;     lf = (lb == 0.f) ? lsig : __logf(lb + (1.0f - lb) * sp); key = (1.0f - lb) * sn;
; __device__ __forceinline__ void w_hg_m1(const Args& a, int l, unsigned char* ws, const bf16_t* proj, LAS unsigned char* wl, int b, int ck_, int h, int lane) {
;     ...
; #pragma unroll
;         for (int tb = 0; tb < 4; ++tb) { float fp[8]; ld8bf(fsrc + (size_t)(16 * tb + lo) * NIN, fp);
;             float kb[8];
; #pragma unroll
;             for (int j = 0; j < 8; ++j) { float lf, key; hg_lf_key(fp[j], lbv[j], lf, key); kb[j] = key * __expf(r63[j] - bb[tb][j]); }
;             *(LAS u32x4*)(kT + (16 * tb + lo) * LD + 32 * kk + 8 * fq) = pack8(kb); }
	v_lshlrev_b32_e32 v60, 16, v4
	v_mul_f32_e64 v26, |v60|, s26
	v_exp_f32_e32 v26, v26
	v_and_b32_e32 v4, 0xffff0000, v4
	v_cmp_le_f32_e32 vcc, 0, v60
	v_cmp_le_f32_e64 s[42:43], 0, v4
	v_add_f32_e32 v27, 1.0, v26
	v_rcp_f32_e32 v28, v27
	v_mul_f32_e64 v27, |v4|, s26
	v_exp_f32_e32 v27, v27
	v_sub_f32_e32 v4, v36, v65
	v_mul_f32_e32 v4, 0x3fb8aa3b, v4
	v_lshlrev_b32_e32 v60, 16, v5
	v_add_f32_e32 v29, 1.0, v27
	v_rcp_f32_e32 v29, v29
	v_and_b32_e32 v63, 0xffff0000, v5
	v_pk_mul_f32 v[26:27], v[26:27], v[28:29]
	s_nop 0
	v_cndmask_b32_e64 v27, v29, v27, s[42:43]
	v_cndmask_b32_e32 v26, v28, v26, vcc
	v_pk_mul_f32 v[26:27], v[22:23], v[26:27]
	v_cmp_le_f32_e32 vcc, 0, v60
	v_pk_mul_f32 v[24:25], v[24:25], v[26:27]
	v_exp_f32_e32 v26, v4
	v_sub_f32_e32 v4, v38, v64
	v_mul_f32_e32 v4, 0x3fb8aa3b, v4
	v_exp_f32_e32 v27, v4
	v_mul_f32_e64 v4, |v60|, s26
	v_exp_f32_e32 v4, v4
	v_cmp_le_f32_e64 s[42:43], 0, v63
	v_cvt_pk_bf16_f32 v24, v24, v25
	v_add_f32_e32 v5, 1.0, v4
	v_rcp_f32_e32 v28, v5
	v_mul_f32_e64 v5, |v63|, s26
	v_exp_f32_e32 v5, v5
	s_nop 0
	v_add_f32_e32 v29, 1.0, v5
	v_rcp_f32_e32 v29, v29
	s_nop 0
	v_pk_mul_f32 v[4:5], v[4:5], v[28:29]
	s_nop 0
	v_cndmask_b32_e64 v5, v29, v5, s[42:43]
	v_cndmask_b32_e32 v4, v28, v4, vcc
	v_pk_mul_f32 v[4:5], v[20:21], v[4:5]
	s_nop 0
	v_pk_mul_f32 v[4:5], v[26:27], v[4:5]
	v_sub_f32_e32 v26, v35, v62
	v_lshlrev_b32_e32 v62, 16, v6
	v_mul_f32_e64 v28, |v62|, s26
	v_exp_f32_e32 v28, v28
	v_and_b32_e32 v6, 0xffff0000, v6
	v_sub_f32_e32 v27, v37, v61
	v_mul_f32_e32 v26, 0x3fb8aa3b, v26
	v_add_f32_e32 v29, 1.0, v28
	v_rcp_f32_e32 v60, v29
	v_mul_f32_e64 v29, |v6|, s26
	v_exp_f32_e32 v29, v29
	v_mul_f32_e32 v27, 0x3fb8aa3b, v27
	v_exp_f32_e32 v26, v26
	v_exp_f32_e32 v27, v27
	v_add_f32_e32 v61, 1.0, v29
	v_rcp_f32_e32 v61, v61
	v_cmp_le_f32_e32 vcc, 0, v62
	v_cmp_le_f32_e64 s[42:43], 0, v6
	v_sub_f32_e32 v6, v39, v59
	v_pk_mul_f32 v[28:29], v[28:29], v[60:61]
	v_mul_f32_e32 v6, 0x3fb8aa3b, v6
	v_cndmask_b32_e64 v29, v61, v29, s[42:43]
	v_cndmask_b32_e32 v28, v60, v28, vcc
	v_pk_mul_f32 v[28:29], v[18:19], v[28:29]
	v_lshlrev_b32_e32 v60, 16, v7
	v_pk_mul_f32 v[26:27], v[26:27], v[28:29]
	v_exp_f32_e32 v28, v6
	v_sub_f32_e32 v6, v40, v58
	v_mul_f32_e32 v6, 0x3fb8aa3b, v6
	v_exp_f32_e32 v29, v6
	v_mul_f32_e64 v6, |v60|, s26
	v_exp_f32_e32 v6, v6
	v_and_b32_e32 v61, 0xffff0000, v7
	v_cmp_le_f32_e32 vcc, 0, v60
	v_cmp_le_f32_e64 s[42:43], 0, v61
	v_add_f32_e32 v7, 1.0, v6
	v_rcp_f32_e32 v58, v7
	v_mul_f32_e64 v7, |v61|, s26
	v_exp_f32_e32 v7, v7
	v_cvt_pk_bf16_f32 v25, v4, v5
	v_cvt_pk_bf16_f32 v26, v26, v27
	v_add_f32_e32 v59, 1.0, v7
	v_rcp_f32_e32 v59, v59
	s_nop 0
	v_pk_mul_f32 v[6:7], v[6:7], v[58:59]
	s_nop 0
	v_cndmask_b32_e64 v7, v59, v7, s[42:43]
	v_cndmask_b32_e32 v6, v58, v6, vcc
	v_pk_mul_f32 v[6:7], v[16:17], v[6:7]
	v_add_co_u32_e32 v4, vcc, s13, v10
	v_pk_mul_f32 v[6:7], v[28:29], v[6:7]
	s_nop 0
	v_addc_co_u32_e32 v5, vcc, 0, v11, vcc
	v_cvt_pk_bf16_f32 v27, v6, v7
	ds_write_b128 v49, v[24:27] offset:11520
	v_mov_b64_e32 v[4:5], v[230:231]
	v_mov_b64_e32 v[6:7], v[232:233]
	v_sub_f32_e32 v25, v31, v56
	v_sub_f32_e32 v24, v1, v57
	v_mul_f32_e32 v24, 0x3fb8aa3b, v24
	v_mul_f32_e32 v25, 0x3fb8aa3b, v25
	v_exp_f32_e32 v24, v24
	v_exp_f32_e32 v25, v25
	s_waitcnt vmcnt(0) lgkmcnt(0)
	v_lshlrev_b32_e32 v56, 16, v4
	v_mul_f32_e64 v26, |v56|, s26
	v_exp_f32_e32 v26, v26
	v_and_b32_e32 v4, 0xffff0000, v4
	v_cmp_le_f32_e32 vcc, 0, v56
	v_cmp_le_f32_e64 s[42:43], 0, v4
	v_add_f32_e32 v27, 1.0, v26
	v_rcp_f32_e32 v28, v27
	v_mul_f32_e64 v27, |v4|, s26
	v_exp_f32_e32 v27, v27
	v_sub_f32_e32 v4, v36, v55
	v_mul_f32_e32 v4, 0x3fb8aa3b, v4
	v_and_b32_e32 v55, 0xffff0000, v5
	v_add_f32_e32 v29, 1.0, v27
	v_rcp_f32_e32 v29, v29
	s_nop 0
	v_pk_mul_f32 v[26:27], v[26:27], v[28:29]
	s_nop 0
	v_cndmask_b32_e64 v27, v29, v27, s[42:43]
	v_cndmask_b32_e32 v26, v28, v26, vcc
	v_pk_mul_f32 v[26:27], v[22:23], v[26:27]
	v_cmp_le_f32_e64 s[42:43], 0, v55
	v_pk_mul_f32 v[24:25], v[24:25], v[26:27]
	v_exp_f32_e32 v26, v4
	v_sub_f32_e32 v4, v38, v54
	v_mul_f32_e32 v4, 0x3fb8aa3b, v4
	v_lshlrev_b32_e32 v54, 16, v5
	v_exp_f32_e32 v27, v4
	v_mul_f32_e64 v4, |v54|, s26
	v_exp_f32_e32 v4, v4
	v_cmp_le_f32_e32 vcc, 0, v54
	v_lshlrev_b32_e32 v54, 16, v6
	v_and_b32_e32 v6, 0xffff0000, v6
	v_add_f32_e32 v5, 1.0, v4
	v_rcp_f32_e32 v28, v5
	v_mul_f32_e64 v5, |v55|, s26
	v_exp_f32_e32 v5, v5
	v_cvt_pk_bf16_f32 v24, v24, v25
	v_add_f32_e32 v29, 1.0, v5
	v_rcp_f32_e32 v29, v29
	s_nop 0
	v_pk_mul_f32 v[4:5], v[4:5], v[28:29]
	s_nop 0
	v_cndmask_b32_e32 v4, v28, v4, vcc
	v_mul_f32_e64 v28, |v54|, s26
	v_exp_f32_e32 v28, v28
	v_cndmask_b32_e64 v5, v29, v5, s[42:43]
	v_pk_mul_f32 v[4:5], v[20:21], v[4:5]
	v_cmp_le_f32_e32 vcc, 0, v54
	v_add_f32_e32 v29, 1.0, v28
	v_pk_mul_f32 v[4:5], v[26:27], v[4:5]
	v_sub_f32_e32 v27, v37, v52
	v_rcp_f32_e32 v52, v29
	v_mul_f32_e64 v29, |v6|, s26
	v_exp_f32_e32 v29, v29
	v_sub_f32_e32 v26, v35, v53
	v_mul_f32_e32 v26, 0x3fb8aa3b, v26
	v_mul_f32_e32 v27, 0x3fb8aa3b, v27
	v_add_f32_e32 v53, 1.0, v29
	v_rcp_f32_e32 v53, v53
	v_exp_f32_e32 v26, v26
	v_exp_f32_e32 v27, v27
	v_cmp_le_f32_e64 s[42:43], 0, v6
	v_pk_mul_f32 v[28:29], v[28:29], v[52:53]
	v_sub_f32_e32 v6, v39, v51
	v_cndmask_b32_e64 v29, v53, v29, s[42:43]
	v_cndmask_b32_e32 v28, v52, v28, vcc
	v_pk_mul_f32 v[28:29], v[18:19], v[28:29]
	v_mul_f32_e32 v6, 0x3fb8aa3b, v6
	v_pk_mul_f32 v[26:27], v[26:27], v[28:29]
	v_exp_f32_e32 v28, v6
	v_sub_f32_e32 v6, v40, v50
	v_mul_f32_e32 v6, 0x3fb8aa3b, v6
	v_lshlrev_b32_e32 v52, 16, v7
	v_exp_f32_e32 v29, v6
	v_mul_f32_e64 v6, |v52|, s26
	v_exp_f32_e32 v6, v6
	v_and_b32_e32 v53, 0xffff0000, v7
	v_cmp_le_f32_e32 vcc, 0, v52
	v_cmp_le_f32_e64 s[42:43], 0, v53
	v_add_f32_e32 v7, 1.0, v6
	v_rcp_f32_e32 v50, v7
	v_mul_f32_e64 v7, |v53|, s26
	v_exp_f32_e32 v7, v7
	v_cvt_pk_bf16_f32 v25, v4, v5
	v_cvt_pk_bf16_f32 v26, v26, v27
	v_add_f32_e32 v51, 1.0, v7
	v_rcp_f32_e32 v51, v51
	s_nop 0
	v_pk_mul_f32 v[6:7], v[6:7], v[50:51]
	s_nop 0
	v_cndmask_b32_e64 v7, v51, v7, s[42:43]
	v_cndmask_b32_e32 v6, v50, v6, vcc
	v_pk_mul_f32 v[6:7], v[16:17], v[6:7]
	v_add_co_u32_e32 v4, vcc, s33, v10
	v_pk_mul_f32 v[6:7], v[28:29], v[6:7]
	s_nop 0
	v_addc_co_u32_e32 v5, vcc, 0, v11, vcc
	v_cvt_pk_bf16_f32 v27, v6, v7
	ds_write_b128 v49, v[24:27] offset:13824
	v_mov_b64_e32 v[4:5], v[234:235]
	v_mov_b64_e32 v[6:7], v[236:237]
	v_sub_f32_e32 v25, v31, v47
	v_sub_f32_e32 v24, v1, v48
	v_mul_f32_e32 v24, 0x3fb8aa3b, v24
	v_mul_f32_e32 v25, 0x3fb8aa3b, v25
	v_exp_f32_e32 v24, v24
	v_exp_f32_e32 v25, v25
	s_waitcnt vmcnt(0) lgkmcnt(0)
; #define LAS __attribute__((address_space(3)))
; __device__ __forceinline__ u32x4 pack8(const float (&v)[8]) { u32x4 w; w.x = pk2(v[0], v[1]); w.y = pk2(v[2], v[3]); w.z = pk2(v[4], v[5]); w.w = pk2(v[6], v[7]); return w; }
; __device__ __forceinline__ void ld8bf(const bf16_t* p, float (&o)[8]) { unpack8(*(const u32x4*)p, o); }
; __device__ __forceinline__ void w_hg_m1(const Args& a, int l, unsigned char* ws, const bf16_t* proj, LAS unsigned char* wl, int b, int ck_, int h, int lane) {
;     ...
; #pragma unroll
;         for (int tb = 0; tb < 4; ++tb) { float fp[8]; ld8bf(fsrc + (size_t)(16 * tb + lo) * NIN, fp);
;             float kb[8];
; #pragma unroll
;             for (int j = 0; j < 8; ++j) { float lf, key; hg_lf_key(fp[j], lbv[j], lf, key); kb[j] = key * __expf(r63[j] - bb[tb][j]); }
;             *(LAS u32x4*)(kT + (16 * tb + lo) * LD + 32 * kk + 8 * fq) = pack8(kb); }
;         if (lo == 0) { float* dp = (float*)(ws + WS_HGDEC) + (size_t)((b * NCH + ck_) * 4 + h) * 64 + 32 * kk + 8 * fq;
; #pragma unroll
;             for (int j = 0; j < 8; ++j) dp[j] = __expf(r63[j]); }
	v_lshlrev_b32_e32 v47, 16, v4
	v_mul_f32_e64 v26, |v47|, s26
	v_exp_f32_e32 v26, v26
	v_and_b32_e32 v4, 0xffff0000, v4
	v_cmp_le_f32_e32 vcc, 0, v47
	v_cmp_le_f32_e64 s[42:43], 0, v4
	v_add_f32_e32 v27, 1.0, v26
	v_rcp_f32_e32 v28, v27
	v_mul_f32_e64 v27, |v4|, s26
	v_exp_f32_e32 v27, v27
	v_sub_f32_e32 v4, v36, v46
	v_mul_f32_e32 v4, 0x3fb8aa3b, v4
	v_add_f32_e32 v29, 1.0, v27
	v_rcp_f32_e32 v29, v29
	s_nop 0
	v_pk_mul_f32 v[26:27], v[26:27], v[28:29]
	s_nop 0
	v_cndmask_b32_e64 v27, v29, v27, s[42:43]
	v_cndmask_b32_e32 v26, v28, v26, vcc
	v_pk_mul_f32 v[22:23], v[22:23], v[26:27]
	v_lshlrev_b32_e32 v28, 16, v5
	v_pk_mul_f32 v[22:23], v[24:25], v[22:23]
	v_exp_f32_e32 v24, v4
	v_sub_f32_e32 v4, v38, v45
	v_mul_f32_e32 v4, 0x3fb8aa3b, v4
	v_exp_f32_e32 v25, v4
	v_mul_f32_e64 v4, |v28|, s26
	v_exp_f32_e32 v4, v4
	v_and_b32_e32 v29, 0xffff0000, v5
	v_cmp_le_f32_e32 vcc, 0, v28
	v_cmp_le_f32_e64 s[42:43], 0, v29
	v_add_f32_e32 v5, 1.0, v4
	v_rcp_f32_e32 v26, v5
	v_mul_f32_e64 v5, |v29|, s26
	v_exp_f32_e32 v5, v5
	v_lshlrev_b32_e32 v28, 16, v6
	v_and_b32_e32 v6, 0xffff0000, v6
	v_add_f32_e32 v27, 1.0, v5
	v_rcp_f32_e32 v27, v27
	s_nop 0
	v_pk_mul_f32 v[4:5], v[4:5], v[26:27]
	s_nop 0
	v_cndmask_b32_e64 v5, v27, v5, s[42:43]
	v_cndmask_b32_e32 v4, v26, v4, vcc
	v_pk_mul_f32 v[4:5], v[20:21], v[4:5]
	v_sub_f32_e32 v20, v35, v44
	v_pk_mul_f32 v[4:5], v[24:25], v[4:5]
	v_mul_f32_e64 v24, |v28|, s26
	v_exp_f32_e32 v24, v24
	v_sub_f32_e32 v21, v37, v43
	v_mul_f32_e32 v20, 0x3fb8aa3b, v20
	v_mul_f32_e32 v21, 0x3fb8aa3b, v21
	v_add_f32_e32 v25, 1.0, v24
	v_rcp_f32_e32 v26, v25
	v_mul_f32_e64 v25, |v6|, s26
	v_exp_f32_e32 v25, v25
	v_exp_f32_e32 v20, v20
	v_exp_f32_e32 v21, v21
	v_cmp_le_f32_e32 vcc, 0, v28
	v_add_f32_e32 v27, 1.0, v25
	v_rcp_f32_e32 v27, v27
	v_cmp_le_f32_e64 s[42:43], 0, v6
	v_sub_f32_e32 v6, v39, v42
	v_mul_f32_e32 v6, 0x3fb8aa3b, v6
	v_pk_mul_f32 v[24:25], v[24:25], v[26:27]
	s_nop 0
	v_cndmask_b32_e64 v25, v27, v25, s[42:43]
	v_cndmask_b32_e32 v24, v26, v24, vcc
	v_pk_mul_f32 v[18:19], v[18:19], v[24:25]
	v_lshlrev_b32_e32 v26, 16, v7
	v_pk_mul_f32 v[18:19], v[20:21], v[18:19]
	v_exp_f32_e32 v20, v6
	v_sub_f32_e32 v6, v40, v41
	v_mul_f32_e32 v6, 0x3fb8aa3b, v6
	v_exp_f32_e32 v21, v6
	v_mul_f32_e64 v6, |v26|, s26
	v_exp_f32_e32 v6, v6
	v_and_b32_e32 v27, 0xffff0000, v7
	v_cmp_le_f32_e32 vcc, 0, v26
	v_cmp_le_f32_e64 s[42:43], 0, v27
	v_add_f32_e32 v7, 1.0, v6
	v_rcp_f32_e32 v24, v7
	v_mul_f32_e64 v7, |v27|, s26
	v_exp_f32_e32 v7, v7
	v_cvt_pk_bf16_f32 v18, v18, v19
	v_add_f32_e32 v25, 1.0, v7
	v_rcp_f32_e32 v25, v25
	s_nop 0
	v_pk_mul_f32 v[6:7], v[6:7], v[24:25]
	s_nop 0
	v_cndmask_b32_e64 v7, v25, v7, s[42:43]
	v_cndmask_b32_e32 v6, v24, v6, vcc
	v_pk_mul_f32 v[6:7], v[16:17], v[6:7]
	v_cvt_pk_bf16_f32 v16, v22, v23
	v_pk_mul_f32 v[6:7], v[20:21], v[6:7]
	v_cvt_pk_bf16_f32 v17, v4, v5
	v_cvt_pk_bf16_f32 v19, v6, v7
	ds_write_b128 v49, v[16:19] offset:16128
	s_and_saveexec_b64 s[34:35], s[38:39]
	s_cbranch_execz .LBB0_671
	v_mul_f32_e32 v1, 0x3fb8aa3b, v1
	v_exp_f32_e32 v4, v1
	v_mul_f32_e32 v1, 0x3fb8aa3b, v31
	v_exp_f32_e32 v5, v1
	v_mul_f32_e32 v1, 0x3fb8aa3b, v36
	v_exp_f32_e32 v6, v1
	v_mul_f32_e32 v1, 0x3fb8aa3b, v38
	v_exp_f32_e32 v7, v1
	v_mul_f32_e32 v1, 0x3fb8aa3b, v35
	global_store_dwordx4 v[8:9], v[4:7], off
	s_nop 1
	v_exp_f32_e32 v4, v1
	v_mul_f32_e32 v1, 0x3fb8aa3b, v37
	v_exp_f32_e32 v5, v1
	v_mul_f32_e32 v1, 0x3fb8aa3b, v39
	v_exp_f32_e32 v6, v1
	v_mul_f32_e32 v1, 0x3fb8aa3b, v40
	v_exp_f32_e32 v7, v1
	global_store_dwordx4 v[8:9], v[4:7], off offset:16

; __device__ __forceinline__ float row_sum_incl(float v) { v += dpp_shr0<1>(v); v += dpp_shr0<2>(v); v += dpp_shr0<4>(v); v += dpp_shr0<8>(v); return v; }
; __device__ __forceinline__ float bcast15(float v, int lane) { return bperm_f((lane & 48) | 15, v); }
; __device__ __forceinline__ void w_hg_scan(const float (&lbv)[8], const bf16_t* fsrc, int lane, float (&bb)[4][8], float (&r31)[8], float (&r63)[8]) {
;     ...
;     for (int j = 0; j < 8; ++j) carry[j] = 0.f;
; #pragma unroll
;     for (int tb = 0; tb < 4; ++tb) {
; #pragma unroll
;         for (int j = 0; j < 8; ++j) { const float v = row_sum_incl(bb[tb][j]) + carry[j]; bb[tb][j] = v; carry[j] = bcast15(v, lane); if (tb == 1) r31[j] = carry[j]; if (tb == 3) r63[j] = carry[j]; }
;         __builtin_amdgcn_sched_barrier(0);
;     }
.LBB0_808:
	s_or_b64 exec, exec, s[34:35]
	v_add_f32_dpp v1, v22, v22 row_shr:1 row_mask:0xf bank_mask:0xf bound_ctrl:1
	v_add_f32_dpp v22, v24, v24 row_shr:1 row_mask:0xf bank_mask:0xf bound_ctrl:1
	v_or_b32_e32 v30, 60, v30
	v_add_f32_dpp v1, v1, v1 row_shr:2 row_mask:0xf bank_mask:0xf bound_ctrl:1
	v_add_f32_dpp v22, v22, v22 row_shr:2 row_mask:0xf bank_mask:0xf bound_ctrl:1
	s_mov_b64 s[20:21], 0x18000
	v_add_f32_dpp v1, v1, v1 row_shr:4 row_mask:0xf bank_mask:0xf bound_ctrl:1
	v_add_f32_dpp v22, v22, v22 row_shr:4 row_mask:0xf bank_mask:0xf bound_ctrl:1
	v_mul_u32_u24_e32 v68, 0x90, v34
	v_add_f32_dpp v1, v1, v1 row_shr:8 row_mask:0xf bank_mask:0xf bound_ctrl:1
	v_add_f32_dpp v22, v22, v22 row_shr:8 row_mask:0xf bank_mask:0xf bound_ctrl:1
	v_add_f32_e32 v72, 0, v22
	v_add_f32_e32 v71, 0, v1
	v_add_f32_dpp v22, v25, v25 row_shr:1 row_mask:0xf bank_mask:0xf bound_ctrl:1
	ds_bpermute_b32 v1, v30, v71
	ds_bpermute_b32 v35, v30, v72
	v_add_f32_dpp v22, v22, v22 row_shr:2 row_mask:0xf bank_mask:0xf bound_ctrl:1
	v_lshl_add_u64 v[24:25], v[10:11], 0, s[20:21]
	s_mov_b64 s[20:21], 0x30000
	v_add_f32_dpp v22, v22, v22 row_shr:4 row_mask:0xf bank_mask:0xf bound_ctrl:1
	s_nop 1
	v_add_f32_dpp v22, v22, v22 row_shr:8 row_mask:0xf bank_mask:0xf bound_ctrl:1
	v_add_f32_e32 v73, 0, v22
	ds_bpermute_b32 v37, v30, v73
	v_add_f32_dpp v22, v26, v26 row_shr:1 row_mask:0xf bank_mask:0xf bound_ctrl:1
	s_nop 1
	v_add_f32_dpp v22, v22, v22 row_shr:2 row_mask:0xf bank_mask:0xf bound_ctrl:1
	s_nop 1
	v_add_f32_dpp v22, v22, v22 row_shr:4 row_mask:0xf bank_mask:0xf bound_ctrl:1
	s_nop 1
	v_add_f32_dpp v22, v22, v22 row_shr:8 row_mask:0xf bank_mask:0xf bound_ctrl:1
	v_add_f32_e32 v26, 0, v22
	ds_bpermute_b32 v39, v30, v26
	v_add_f32_dpp v22, v27, v27 row_shr:1 row_mask:0xf bank_mask:0xf bound_ctrl:1
	s_nop 1
	v_add_f32_dpp v22, v22, v22 row_shr:2 row_mask:0xf bank_mask:0xf bound_ctrl:1
	s_nop 1
	v_add_f32_dpp v22, v22, v22 row_shr:4 row_mask:0xf bank_mask:0xf bound_ctrl:1
	s_nop 1
	v_add_f32_dpp v22, v22, v22 row_shr:8 row_mask:0xf bank_mask:0xf bound_ctrl:1
	v_add_f32_e32 v27, 0, v22
	ds_bpermute_b32 v54, v30, v27
	v_add_f32_dpp v22, v28, v28 row_shr:1 row_mask:0xf bank_mask:0xf bound_ctrl:1
	s_nop 1
	v_add_f32_dpp v22, v22, v22 row_shr:2 row_mask:0xf bank_mask:0xf bound_ctrl:1
	s_nop 1
	v_add_f32_dpp v22, v22, v22 row_shr:4 row_mask:0xf bank_mask:0xf bound_ctrl:1
	s_nop 1
	v_add_f32_dpp v22, v22, v22 row_shr:8 row_mask:0xf bank_mask:0xf bound_ctrl:1
	v_add_f32_e32 v28, 0, v22
	ds_bpermute_b32 v55, v30, v28
	v_add_f32_dpp v22, v29, v29 row_shr:1 row_mask:0xf bank_mask:0xf bound_ctrl:1
	s_nop 1
	v_add_f32_dpp v22, v22, v22 row_shr:2 row_mask:0xf bank_mask:0xf bound_ctrl:1
	s_nop 1
	v_add_f32_dpp v22, v22, v22 row_shr:4 row_mask:0xf bank_mask:0xf bound_ctrl:1
	s_nop 1
	v_add_f32_dpp v22, v22, v22 row_shr:8 row_mask:0xf bank_mask:0xf bound_ctrl:1
	v_add_f32_e32 v29, 0, v22
	ds_bpermute_b32 v56, v30, v29
	v_add_f32_dpp v22, v31, v31 row_shr:1 row_mask:0xf bank_mask:0xf bound_ctrl:1
	s_nop 1
	v_add_f32_dpp v22, v22, v22 row_shr:2 row_mask:0xf bank_mask:0xf bound_ctrl:1
	s_nop 1
	v_add_f32_dpp v22, v22, v22 row_shr:4 row_mask:0xf bank_mask:0xf bound_ctrl:1
	s_nop 1
	v_add_f32_dpp v22, v22, v22 row_shr:8 row_mask:0xf bank_mask:0xf bound_ctrl:1
	v_add_f32_e32 v31, 0, v22
	ds_bpermute_b32 v57, v30, v31
	v_lshl_add_u64 v[22:23], v[10:11], 0, s[20:21]
	v_add_f32_dpp v41, v41, v41 row_shr:1 row_mask:0xf bank_mask:0xf bound_ctrl:1
	s_nop 1
	v_add_f32_dpp v41, v41, v41 row_shr:2 row_mask:0xf bank_mask:0xf bound_ctrl:1
	s_nop 1
	v_add_f32_dpp v41, v41, v41 row_shr:4 row_mask:0xf bank_mask:0xf bound_ctrl:1
	s_nop 1
	v_add_f32_dpp v41, v41, v41 row_shr:8 row_mask:0xf bank_mask:0xf bound_ctrl:1
	s_waitcnt lgkmcnt(7)
	v_add_f32_e32 v70, v41, v1
	ds_bpermute_b32 v1, v30, v70
	v_add_f32_dpp v41, v42, v42 row_shr:1 row_mask:0xf bank_mask:0xf bound_ctrl:1
	v_add_f32_dpp v42, v46, v46 row_shr:1 row_mask:0xf bank_mask:0xf bound_ctrl:1
	s_nop 0
	v_add_f32_dpp v41, v41, v41 row_shr:2 row_mask:0xf bank_mask:0xf bound_ctrl:1
	v_add_f32_dpp v42, v42, v42 row_shr:2 row_mask:0xf bank_mask:0xf bound_ctrl:1
	s_nop 0
	v_add_f32_dpp v41, v41, v41 row_shr:4 row_mask:0xf bank_mask:0xf bound_ctrl:1
	v_add_f32_dpp v42, v42, v42 row_shr:4 row_mask:0xf bank_mask:0xf bound_ctrl:1
	s_nop 0
	v_add_f32_dpp v41, v41, v41 row_shr:8 row_mask:0xf bank_mask:0xf bound_ctrl:1
	s_waitcnt lgkmcnt(7)
	v_add_f32_e32 v69, v41, v35
	ds_bpermute_b32 v35, v30, v69
	v_add_f32_dpp v41, v43, v43 row_shr:1 row_mask:0xf bank_mask:0xf bound_ctrl:1
	v_add_f32_dpp v43, v47, v47 row_shr:1 row_mask:0xf bank_mask:0xf bound_ctrl:1
	v_add_f32_dpp v42, v42, v42 row_shr:8 row_mask:0xf bank_mask:0xf bound_ctrl:1
	v_add_f32_dpp v41, v41, v41 row_shr:2 row_mask:0xf bank_mask:0xf bound_ctrl:1
	v_add_f32_dpp v43, v43, v43 row_shr:2 row_mask:0xf bank_mask:0xf bound_ctrl:1
	s_waitcnt lgkmcnt(4)
	v_add_f32_e32 v62, v42, v55
	v_add_f32_dpp v41, v41, v41 row_shr:4 row_mask:0xf bank_mask:0xf bound_ctrl:1
	v_add_f32_dpp v43, v43, v43 row_shr:4 row_mask:0xf bank_mask:0xf bound_ctrl:1
	ds_bpermute_b32 v42, v30, v62
	v_add_f32_dpp v41, v41, v41 row_shr:8 row_mask:0xf bank_mask:0xf bound_ctrl:1
	v_add_f32_e32 v66, v41, v37
	ds_bpermute_b32 v37, v30, v66
	v_add_f32_dpp v41, v44, v44 row_shr:1 row_mask:0xf bank_mask:0xf bound_ctrl:1
	v_add_f32_dpp v44, v48, v48 row_shr:1 row_mask:0xf bank_mask:0xf bound_ctrl:1
	v_add_f32_dpp v43, v43, v43 row_shr:8 row_mask:0xf bank_mask:0xf bound_ctrl:1
	v_add_f32_dpp v41, v41, v41 row_shr:2 row_mask:0xf bank_mask:0xf bound_ctrl:1
	v_add_f32_dpp v44, v44, v44 row_shr:2 row_mask:0xf bank_mask:0xf bound_ctrl:1
	s_waitcnt lgkmcnt(5)
; __device__ __forceinline__ float row_sum_incl(float v) { v += dpp_shr0<1>(v); v += dpp_shr0<2>(v); v += dpp_shr0<4>(v); v += dpp_shr0<8>(v); return v; }
; __device__ __forceinline__ float bcast15(float v, int lane) { return bperm_f((lane & 48) | 15, v); }
; __device__ __forceinline__ void w_hg_scan(const float (&lbv)[8], const bf16_t* fsrc, int lane, float (&bb)[4][8], float (&r31)[8], float (&r63)[8]) {
;     ...
;     for (int tb = 0; tb < 4; ++tb) {
; #pragma unroll
;         for (int j = 0; j < 8; ++j) { const float v = row_sum_incl(bb[tb][j]) + carry[j]; bb[tb][j] = v; carry[j] = bcast15(v, lane); if (tb == 1) r31[j] = carry[j]; if (tb == 3) r63[j] = carry[j]; }
;         __builtin_amdgcn_sched_barrier(0);
;     }
	v_add_f32_e32 v60, v43, v56
	v_add_f32_dpp v41, v41, v41 row_shr:4 row_mask:0xf bank_mask:0xf bound_ctrl:1
	v_add_f32_dpp v44, v44, v44 row_shr:4 row_mask:0xf bank_mask:0xf bound_ctrl:1
	ds_bpermute_b32 v43, v30, v60
	v_add_f32_dpp v41, v41, v41 row_shr:8 row_mask:0xf bank_mask:0xf bound_ctrl:1
	v_add_f32_e32 v65, v41, v39
	ds_bpermute_b32 v39, v30, v65
	v_add_f32_dpp v41, v45, v45 row_shr:1 row_mask:0xf bank_mask:0xf bound_ctrl:1
	v_add_f32_dpp v44, v44, v44 row_shr:8 row_mask:0xf bank_mask:0xf bound_ctrl:1
	s_waitcnt lgkmcnt(6)
	v_add_f32_e32 v59, v44, v57
	v_add_f32_dpp v41, v41, v41 row_shr:2 row_mask:0xf bank_mask:0xf bound_ctrl:1
	ds_bpermute_b32 v44, v30, v59
	s_nop 0
	v_add_f32_dpp v41, v41, v41 row_shr:4 row_mask:0xf bank_mask:0xf bound_ctrl:1
	s_nop 1
	v_add_f32_dpp v41, v41, v41 row_shr:8 row_mask:0xf bank_mask:0xf bound_ctrl:1
	v_add_f32_e32 v63, v41, v54
	ds_bpermute_b32 v41, v30, v63
	v_add_f32_dpp v45, v49, v49 row_shr:1 row_mask:0xf bank_mask:0xf bound_ctrl:1
	s_nop 1
	v_add_f32_dpp v45, v45, v45 row_shr:2 row_mask:0xf bank_mask:0xf bound_ctrl:1
	s_nop 1
	v_add_f32_dpp v45, v45, v45 row_shr:4 row_mask:0xf bank_mask:0xf bound_ctrl:1
	s_nop 1
	v_add_f32_dpp v45, v45, v45 row_shr:8 row_mask:0xf bank_mask:0xf bound_ctrl:1
	s_waitcnt lgkmcnt(7)
	v_add_f32_e32 v57, v45, v1
	ds_bpermute_b32 v1, v30, v57
	v_add_f32_dpp v45, v50, v50 row_shr:1 row_mask:0xf bank_mask:0xf bound_ctrl:1
	s_nop 1
	v_add_f32_dpp v45, v45, v45 row_shr:2 row_mask:0xf bank_mask:0xf bound_ctrl:1
	s_nop 1
	v_add_f32_dpp v45, v45, v45 row_shr:4 row_mask:0xf bank_mask:0xf bound_ctrl:1
	s_nop 1
	v_add_f32_dpp v45, v45, v45 row_shr:8 row_mask:0xf bank_mask:0xf bound_ctrl:1
	s_waitcnt lgkmcnt(7)
	v_add_f32_e32 v56, v45, v35
	ds_bpermute_b32 v35, v30, v56
	v_add_f32_dpp v45, v51, v51 row_shr:1 row_mask:0xf bank_mask:0xf bound_ctrl:1
	s_nop 1
	v_add_f32_dpp v45, v45, v45 row_shr:2 row_mask:0xf bank_mask:0xf bound_ctrl:1
	s_nop 1
	v_add_f32_dpp v45, v45, v45 row_shr:4 row_mask:0xf bank_mask:0xf bound_ctrl:1
	s_nop 1
	v_add_f32_dpp v45, v45, v45 row_shr:8 row_mask:0xf bank_mask:0xf bound_ctrl:1
	s_waitcnt lgkmcnt(6)
	v_add_f32_e32 v55, v45, v37
	ds_bpermute_b32 v37, v30, v55
	v_add_f32_dpp v45, v52, v52 row_shr:1 row_mask:0xf bank_mask:0xf bound_ctrl:1
	s_nop 1
	v_add_f32_dpp v45, v45, v45 row_shr:2 row_mask:0xf bank_mask:0xf bound_ctrl:1
	s_nop 1
	v_add_f32_dpp v45, v45, v45 row_shr:4 row_mask:0xf bank_mask:0xf bound_ctrl:1
	s_nop 1
	v_add_f32_dpp v45, v45, v45 row_shr:8 row_mask:0xf bank_mask:0xf bound_ctrl:1
	s_waitcnt lgkmcnt(5)
	v_add_f32_e32 v54, v45, v39
	ds_bpermute_b32 v39, v30, v54
	v_add_f32_dpp v45, v53, v53 row_shr:1 row_mask:0xf bank_mask:0xf bound_ctrl:1
	s_nop 1
	v_add_f32_dpp v45, v45, v45 row_shr:2 row_mask:0xf bank_mask:0xf bound_ctrl:1
	s_nop 1
	v_add_f32_dpp v45, v45, v45 row_shr:4 row_mask:0xf bank_mask:0xf bound_ctrl:1
	s_nop 1
	v_add_f32_dpp v45, v45, v45 row_shr:8 row_mask:0xf bank_mask:0xf bound_ctrl:1
	s_waitcnt lgkmcnt(4)
	v_add_f32_e32 v53, v45, v41
	ds_bpermute_b32 v41, v30, v53
	v_add_f32_dpp v45, v58, v58 row_shr:1 row_mask:0xf bank_mask:0xf bound_ctrl:1
	s_nop 1
	v_add_f32_dpp v45, v45, v45 row_shr:2 row_mask:0xf bank_mask:0xf bound_ctrl:1
	s_nop 1
	v_add_f32_dpp v45, v45, v45 row_shr:4 row_mask:0xf bank_mask:0xf bound_ctrl:1
	s_nop 1
	v_add_f32_dpp v45, v45, v45 row_shr:8 row_mask:0xf bank_mask:0xf bound_ctrl:1
	v_add_f32_e32 v52, v45, v42
	ds_bpermute_b32 v42, v30, v52
	v_add_f32_dpp v45, v61, v61 row_shr:1 row_mask:0xf bank_mask:0xf bound_ctrl:1
	s_nop 1
	v_add_f32_dpp v45, v45, v45 row_shr:2 row_mask:0xf bank_mask:0xf bound_ctrl:1
	s_nop 1
	v_add_f32_dpp v45, v45, v45 row_shr:4 row_mask:0xf bank_mask:0xf bound_ctrl:1
	s_nop 1
	v_add_f32_dpp v45, v45, v45 row_shr:8 row_mask:0xf bank_mask:0xf bound_ctrl:1
	v_add_f32_e32 v51, v45, v43
	ds_bpermute_b32 v43, v30, v51
	v_add_f32_dpp v45, v64, v64 row_shr:1 row_mask:0xf bank_mask:0xf bound_ctrl:1
	s_nop 1
	v_add_f32_dpp v45, v45, v45 row_shr:2 row_mask:0xf bank_mask:0xf bound_ctrl:1
	s_nop 1
	v_add_f32_dpp v45, v45, v45 row_shr:4 row_mask:0xf bank_mask:0xf bound_ctrl:1
	s_nop 1
	v_add_f32_dpp v45, v45, v45 row_shr:8 row_mask:0xf bank_mask:0xf bound_ctrl:1
	v_add_f32_e32 v50, v45, v44
	ds_bpermute_b32 v58, v30, v50
	v_add_f32_dpp v4, v4, v4 row_shr:1 row_mask:0xf bank_mask:0xf bound_ctrl:1
	v_add_f32_dpp v44, v67, v67 row_shr:1 row_mask:0xf bank_mask:0xf bound_ctrl:1
	s_nop 0
	v_add_f32_dpp v4, v4, v4 row_shr:2 row_mask:0xf bank_mask:0xf bound_ctrl:1
	v_add_f32_dpp v44, v44, v44 row_shr:2 row_mask:0xf bank_mask:0xf bound_ctrl:1
	s_nop 0
	v_add_f32_dpp v4, v4, v4 row_shr:4 row_mask:0xf bank_mask:0xf bound_ctrl:1
	v_add_f32_dpp v44, v44, v44 row_shr:4 row_mask:0xf bank_mask:0xf bound_ctrl:1
	s_nop 0
	v_add_f32_dpp v4, v4, v4 row_shr:8 row_mask:0xf bank_mask:0xf bound_ctrl:1
	s_waitcnt lgkmcnt(6)
	v_add_f32_e32 v48, v4, v35
	v_add_f32_dpp v44, v44, v44 row_shr:8 row_mask:0xf bank_mask:0xf bound_ctrl:1
	v_add_f32_dpp v4, v36, v36 row_shr:1 row_mask:0xf bank_mask:0xf bound_ctrl:1
	v_add_f32_e32 v49, v44, v1
	ds_bpermute_b32 v1, v30, v49
	v_add_f32_dpp v4, v4, v4 row_shr:2 row_mask:0xf bank_mask:0xf bound_ctrl:1
	ds_bpermute_b32 v35, v30, v48
	s_nop 0
	v_add_f32_dpp v4, v4, v4 row_shr:4 row_mask:0xf bank_mask:0xf bound_ctrl:1
	s_nop 1
	v_add_f32_dpp v4, v4, v4 row_shr:8 row_mask:0xf bank_mask:0xf bound_ctrl:1
	s_waitcnt lgkmcnt(7)
	v_add_f32_e32 v47, v4, v37
	ds_bpermute_b32 v37, v30, v47
	v_add_f32_dpp v4, v5, v5 row_shr:1 row_mask:0xf bank_mask:0xf bound_ctrl:1
	s_nop 1
	v_add_f32_dpp v4, v4, v4 row_shr:2 row_mask:0xf bank_mask:0xf bound_ctrl:1
	s_nop 1
	v_add_f32_dpp v4, v4, v4 row_shr:4 row_mask:0xf bank_mask:0xf bound_ctrl:1
	s_nop 1
	v_add_f32_dpp v4, v4, v4 row_shr:8 row_mask:0xf bank_mask:0xf bound_ctrl:1
	s_waitcnt lgkmcnt(7)
; #define LAS __attribute__((address_space(3)))
; __device__ __forceinline__ u32x4 pack8(const float (&v)[8]) { u32x4 w; w.x = pk2(v[0], v[1]); w.y = pk2(v[2], v[3]); w.z = pk2(v[4], v[5]); w.w = pk2(v[6], v[7]); return w; }
; __device__ __forceinline__ void ld8bf(const bf16_t* p, float (&o)[8]) { unpack8(*(const u32x4*)p, o); }
; __device__ __forceinline__ float row_sum_incl(float v) { v += dpp_shr0<1>(v); v += dpp_shr0<2>(v); v += dpp_shr0<4>(v); v += dpp_shr0<8>(v); return v; }
; __device__ __forceinline__ float bcast15(float v, int lane) { return bperm_f((lane & 48) | 15, v); }
; __device__ __forceinline__ void w_hg_scan(const float (&lbv)[8], const bf16_t* fsrc, int lane, float (&bb)[4][8], float (&r31)[8], float (&r63)[8]) {
;     ...
;     for (int tb = 0; tb < 4; ++tb) {
; #pragma unroll
;         for (int j = 0; j < 8; ++j) { const float v = row_sum_incl(bb[tb][j]) + carry[j]; bb[tb][j] = v; carry[j] = bcast15(v, lane); if (tb == 1) r31[j] = carry[j]; if (tb == 3) r63[j] = carry[j]; }
;         __builtin_amdgcn_sched_barrier(0);
;     }
; __device__ __forceinline__ void w_hg_m1(const Args& a, int l, unsigned char* ws, const bf16_t* proj, LAS unsigned char* wl, int b, int ck_, int h, int lane) {
;     ...
; #pragma unroll
;         for (int tb = 0; tb < 4; ++tb) { float fp[8]; ld8bf(fsrc + (size_t)(16 * tb + lo) * NIN, fp);
;             float kb[8];
; #pragma unroll
;             for (int j = 0; j < 8; ++j) { float lf, key; hg_lf_key(fp[j], lbv[j], lf, key); kb[j] = key * __expf(r63[j] - bb[tb][j]); }
;             *(LAS u32x4*)(kT + (16 * tb + lo) * LD + 32 * kk + 8 * fq) = pack8(kb); }
	v_add_f32_e32 v46, v4, v39
	ds_bpermute_b32 v39, v30, v46
	v_add_f32_dpp v4, v38, v38 row_shr:1 row_mask:0xf bank_mask:0xf bound_ctrl:1
	s_nop 1
	v_add_f32_dpp v4, v4, v4 row_shr:2 row_mask:0xf bank_mask:0xf bound_ctrl:1
	s_nop 1
	v_add_f32_dpp v4, v4, v4 row_shr:4 row_mask:0xf bank_mask:0xf bound_ctrl:1
	s_nop 1
	v_add_f32_dpp v4, v4, v4 row_shr:8 row_mask:0xf bank_mask:0xf bound_ctrl:1
	s_waitcnt lgkmcnt(7)
	v_add_f32_e32 v45, v4, v41
	ds_bpermute_b32 v36, v30, v45
	v_add_f32_dpp v4, v6, v6 row_shr:1 row_mask:0xf bank_mask:0xf bound_ctrl:1
	s_nop 1
	v_add_f32_dpp v4, v4, v4 row_shr:2 row_mask:0xf bank_mask:0xf bound_ctrl:1
	s_nop 1
	v_add_f32_dpp v4, v4, v4 row_shr:4 row_mask:0xf bank_mask:0xf bound_ctrl:1
	s_nop 1
	v_add_f32_dpp v4, v4, v4 row_shr:8 row_mask:0xf bank_mask:0xf bound_ctrl:1
	s_waitcnt lgkmcnt(7)
	v_add_f32_e32 v44, v4, v42
	ds_bpermute_b32 v38, v30, v44
	v_add_f32_dpp v4, v40, v40 row_shr:1 row_mask:0xf bank_mask:0xf bound_ctrl:1
	s_nop 1
	v_add_f32_dpp v4, v4, v4 row_shr:2 row_mask:0xf bank_mask:0xf bound_ctrl:1
	s_nop 1
	v_add_f32_dpp v4, v4, v4 row_shr:4 row_mask:0xf bank_mask:0xf bound_ctrl:1
	s_nop 1
	v_add_f32_dpp v4, v4, v4 row_shr:8 row_mask:0xf bank_mask:0xf bound_ctrl:1
	s_waitcnt lgkmcnt(7)
	v_add_f32_e32 v43, v4, v43
	ds_bpermute_b32 v40, v30, v43
	v_add_f32_dpp v4, v7, v7 row_shr:1 row_mask:0xf bank_mask:0xf bound_ctrl:1
	s_nop 1
	v_add_f32_dpp v4, v4, v4 row_shr:2 row_mask:0xf bank_mask:0xf bound_ctrl:1
	s_nop 1
	v_add_f32_dpp v4, v4, v4 row_shr:4 row_mask:0xf bank_mask:0xf bound_ctrl:1
	s_nop 1
	v_add_f32_dpp v4, v4, v4 row_shr:8 row_mask:0xf bank_mask:0xf bound_ctrl:1
	s_waitcnt lgkmcnt(7)
	v_add_f32_e32 v42, v4, v58
	ds_bpermute_b32 v41, v30, v42
	v_mov_b64_e32 v[4:5], v[238:239]
	v_mov_b64_e32 v[6:7], v[240:241]
	s_waitcnt lgkmcnt(0)
	v_sub_f32_e32 v30, v37, v73
	v_sub_f32_e32 v26, v39, v26
	v_sub_f32_e32 v27, v36, v27
	v_pk_add_f32 v[14:15], v[20:21], 1.0 op_sel_hi:[1,0] neg_lo:[1,0] neg_hi:[1,0]
	v_sub_f32_e32 v20, v1, v71
	v_sub_f32_e32 v28, v38, v28
	v_sub_f32_e32 v29, v40, v29
	v_mul_f32_e32 v30, 0x3fb8aa3b, v30
	v_mul_f32_e32 v58, 0x3fb8aa3b, v26
	v_mul_f32_e32 v61, 0x3fb8aa3b, v27
	v_sub_f32_e32 v31, v41, v31
	v_mul_f32_e32 v20, 0x3fb8aa3b, v20
	v_mul_f32_e32 v64, 0x3fb8aa3b, v28
	v_mul_f32_e32 v67, 0x3fb8aa3b, v29
	v_exp_f32_e32 v28, v30
	v_exp_f32_e32 v29, v58
	v_exp_f32_e32 v30, v61
	v_sub_f32_e32 v21, v35, v72
	v_mul_f32_e32 v71, 0x3fb8aa3b, v31
	v_exp_f32_e32 v26, v20
	v_exp_f32_e32 v31, v64
	v_exp_f32_e32 v20, v67
	v_mul_f32_e32 v21, 0x3fb8aa3b, v21
	v_exp_f32_e32 v27, v21
	v_exp_f32_e32 v21, v71
	v_pk_add_f32 v[18:19], v[18:19], 1.0 op_sel_hi:[1,0] neg_lo:[1,0] neg_hi:[1,0]
	v_pk_add_f32 v[16:17], v[16:17], 1.0 op_sel_hi:[1,0] neg_lo:[1,0] neg_hi:[1,0]
	v_add_u32_e32 v2, v2, v68
	s_waitcnt vmcnt(0)
	v_lshlrev_b32_e32 v58, 16, v4
	v_and_b32_e32 v61, 0xffff0000, v4
	v_lshlrev_b32_e32 v64, 16, v5
	v_and_b32_e32 v67, 0xffff0000, v5
	v_mul_f32_e64 v4, |v58|, s26
	v_mul_f32_e64 v5, |v61|, s26
	v_exp_f32_e32 v4, v4
	v_exp_f32_e32 v5, v5
	v_lshlrev_b32_e32 v71, 16, v6
	v_and_b32_e32 v84, 0xffff0000, v6
	v_lshlrev_b32_e32 v85, 16, v7
	v_and_b32_e32 v86, 0xffff0000, v7
	v_mul_f32_e64 v6, |v64|, s26
	v_mul_f32_e64 v7, |v67|, s26
	v_exp_f32_e32 v6, v6
	v_exp_f32_e32 v7, v7
	v_mul_f32_e64 v72, |v71|, s26
	v_mul_f32_e64 v73, |v84|, s26
	v_exp_f32_e32 v72, v72
	v_exp_f32_e32 v73, v73
	v_add_f32_e32 v76, 1.0, v4
	v_add_f32_e32 v77, 1.0, v5
	v_mul_f32_e64 v74, |v85|, s26
	v_mul_f32_e64 v75, |v86|, s26
	v_rcp_f32_e32 v76, v76
	v_rcp_f32_e32 v77, v77
	v_exp_f32_e32 v74, v74
	v_exp_f32_e32 v75, v75
	v_add_f32_e32 v78, 1.0, v6
	v_add_f32_e32 v79, 1.0, v7
	v_rcp_f32_e32 v78, v78
	v_rcp_f32_e32 v79, v79
	v_add_f32_e32 v80, 1.0, v72
	v_add_f32_e32 v81, 1.0, v73
	v_rcp_f32_e32 v80, v80
	v_rcp_f32_e32 v81, v81
	v_pk_mul_f32 v[4:5], v[4:5], v[76:77]
	v_cmp_le_f32_e32 vcc, 0, v61
	v_add_f32_e32 v82, 1.0, v74
	v_add_f32_e32 v83, 1.0, v75
	v_cndmask_b32_e32 v5, v77, v5, vcc
	v_cmp_le_f32_e32 vcc, 0, v58
	v_rcp_f32_e32 v82, v82
	v_rcp_f32_e32 v83, v83
	v_pk_mul_f32 v[6:7], v[6:7], v[78:79]
	v_cndmask_b32_e32 v4, v76, v4, vcc
	v_cmp_le_f32_e32 vcc, 0, v67
	v_pk_mul_f32 v[72:73], v[72:73], v[80:81]
	v_pk_mul_f32 v[74:75], v[74:75], v[82:83]
	v_cndmask_b32_e32 v7, v79, v7, vcc
	v_cmp_le_f32_e32 vcc, 0, v64
	v_pk_mul_f32 v[4:5], v[14:15], v[4:5]
	s_nop 0
	v_cndmask_b32_e32 v6, v78, v6, vcc
	v_cmp_le_f32_e32 vcc, 0, v84
	v_pk_mul_f32 v[6:7], v[18:19], v[6:7]
	v_pk_mul_f32 v[4:5], v[26:27], v[4:5]
	v_cndmask_b32_e32 v73, v81, v73, vcc
	v_cmp_le_f32_e32 vcc, 0, v71
	v_pk_mul_f32 v[6:7], v[28:29], v[6:7]
	v_cvt_pk_bf16_f32 v4, v4, v5
	v_cndmask_b32_e32 v72, v80, v72, vcc
	v_cmp_le_f32_e32 vcc, 0, v86
	v_pk_mul_f32 v[72:73], v[16:17], v[72:73]
	v_cvt_pk_bf16_f32 v5, v6, v7
	v_cndmask_b32_e32 v75, v83, v75, vcc
	v_cmp_le_f32_e32 vcc, 0, v85
	v_pk_mul_f32 v[26:27], v[30:31], v[72:73]
	v_sub_f32_e32 v28, v40, v60
	v_cndmask_b32_e32 v74, v82, v74, vcc
	v_pk_mul_f32 v[74:75], v[12:13], v[74:75]
	v_cvt_pk_bf16_f32 v6, v26, v27
	v_pk_mul_f32 v[20:21], v[20:21], v[74:75]
	v_sub_f32_e32 v26, v36, v63
	v_cvt_pk_bf16_f32 v7, v20, v21
	ds_write_b128 v2, v[4:7] offset:9280
	v_mov_b64_e32 v[4:5], v[242:243]
	v_mov_b64_e32 v[6:7], v[244:245]
	v_sub_f32_e32 v11, v35, v69
	v_sub_f32_e32 v10, v1, v70
	v_sub_f32_e32 v20, v37, v66
	v_sub_f32_e32 v21, v39, v65
	v_sub_f32_e32 v27, v38, v62
	v_sub_f32_e32 v29, v41, v59
	v_mul_f32_e32 v30, 0x3fb8aa3b, v20
	v_mul_f32_e32 v31, 0x3fb8aa3b, v21
	v_mul_f32_e32 v10, 0x3fb8aa3b, v10
	v_mul_f32_e32 v11, 0x3fb8aa3b, v11
	v_mul_f32_e32 v58, 0x3fb8aa3b, v26
	v_mul_f32_e32 v59, 0x3fb8aa3b, v27
	v_mul_f32_e32 v60, 0x3fb8aa3b, v28
	v_mul_f32_e32 v61, 0x3fb8aa3b, v29
	v_exp_f32_e32 v26, v30
	v_exp_f32_e32 v27, v31
	v_exp_f32_e32 v20, v10
	v_exp_f32_e32 v21, v11
	v_exp_f32_e32 v10, v60
	v_exp_f32_e32 v11, v61
	v_exp_f32_e32 v28, v58
	v_exp_f32_e32 v29, v59
	s_waitcnt vmcnt(0) lgkmcnt(0)
; #define LAS __attribute__((address_space(3)))
; __device__ __forceinline__ u32x4 pack8(const float (&v)[8]) { u32x4 w; w.x = pk2(v[0], v[1]); w.y = pk2(v[2], v[3]); w.z = pk2(v[4], v[5]); w.w = pk2(v[6], v[7]); return w; }
; __device__ __forceinline__ void ld8bf(const bf16_t* p, float (&o)[8]) { unpack8(*(const u32x4*)p, o); }
; __device__ __forceinline__ void hg_lf_key(float fp, float lb, float& lf, float& key) {
;     const float e = __expf(-fabsf(fp));
;     const float rc = __builtin_amdgcn_rcpf(1.0f + e);
;     const float sp = fp >= 0.f ? rc : e * rc;
;     const float sn = fp >= 0.f ? e * rc : rc;
;     const float lsig = (fp >= 0.f ? 0.f : fp) + __logf(rc);
;     lf = (lb == 0.f) ? lsig : __logf(lb + (1.0f - lb) * sp); key = (1.0f - lb) * sn;
; __device__ __forceinline__ void w_hg_m1(const Args& a, int l, unsigned char* ws, const bf16_t* proj, LAS unsigned char* wl, int b, int ck_, int h, int lane) {
;     ...
; #pragma unroll
;         for (int tb = 0; tb < 4; ++tb) { float fp[8]; ld8bf(fsrc + (size_t)(16 * tb + lo) * NIN, fp);
;             float kb[8];
; #pragma unroll
;             for (int j = 0; j < 8; ++j) { float lf, key; hg_lf_key(fp[j], lbv[j], lf, key); kb[j] = key * __expf(r63[j] - bb[tb][j]); }
;             *(LAS u32x4*)(kT + (16 * tb + lo) * LD + 32 * kk + 8 * fq) = pack8(kb); }
	v_lshlrev_b32_e32 v68, 16, v4
	v_and_b32_e32 v69, 0xffff0000, v4
	v_lshlrev_b32_e32 v70, 16, v5
	v_and_b32_e32 v71, 0xffff0000, v5
	v_mul_f32_e64 v4, |v68|, s26
	v_mul_f32_e64 v5, |v69|, s26
	v_exp_f32_e32 v4, v4
	v_exp_f32_e32 v5, v5
	v_lshlrev_b32_e32 v72, 16, v6
	v_and_b32_e32 v73, 0xffff0000, v6
	v_lshlrev_b32_e32 v74, 16, v7
	v_and_b32_e32 v75, 0xffff0000, v7
	v_mul_f32_e64 v6, |v70|, s26
	v_mul_f32_e64 v7, |v71|, s26
	v_exp_f32_e32 v6, v6
	v_exp_f32_e32 v7, v7
	v_mul_f32_e64 v30, |v72|, s26
	v_mul_f32_e64 v31, |v73|, s26
	v_exp_f32_e32 v30, v30
	v_exp_f32_e32 v31, v31
	v_add_f32_e32 v60, 1.0, v4
	v_add_f32_e32 v61, 1.0, v5
	v_mul_f32_e64 v58, |v74|, s26
	v_mul_f32_e64 v59, |v75|, s26
	v_rcp_f32_e32 v60, v60
	v_rcp_f32_e32 v61, v61
	v_exp_f32_e32 v58, v58
	v_exp_f32_e32 v59, v59
	v_add_f32_e32 v62, 1.0, v6
	v_add_f32_e32 v63, 1.0, v7
	v_rcp_f32_e32 v62, v62
	v_rcp_f32_e32 v63, v63
	v_add_f32_e32 v64, 1.0, v30
	v_add_f32_e32 v65, 1.0, v31
	v_rcp_f32_e32 v64, v64
	v_rcp_f32_e32 v65, v65
	v_pk_mul_f32 v[4:5], v[4:5], v[60:61]
	v_cmp_le_f32_e32 vcc, 0, v69
	v_add_f32_e32 v66, 1.0, v58
	v_add_f32_e32 v67, 1.0, v59
	v_cndmask_b32_e32 v5, v61, v5, vcc
	v_cmp_le_f32_e32 vcc, 0, v68
	v_rcp_f32_e32 v66, v66
	v_rcp_f32_e32 v67, v67
	v_pk_mul_f32 v[6:7], v[6:7], v[62:63]
	v_cndmask_b32_e32 v4, v60, v4, vcc
	v_cmp_le_f32_e32 vcc, 0, v71
	v_pk_mul_f32 v[30:31], v[30:31], v[64:65]
	v_pk_mul_f32 v[58:59], v[58:59], v[66:67]
	v_cndmask_b32_e32 v7, v63, v7, vcc
	v_cmp_le_f32_e32 vcc, 0, v70
	v_pk_mul_f32 v[4:5], v[14:15], v[4:5]
	s_nop 0
	v_cndmask_b32_e32 v6, v62, v6, vcc
	v_cmp_le_f32_e32 vcc, 0, v73
	v_pk_mul_f32 v[6:7], v[18:19], v[6:7]
	v_pk_mul_f32 v[4:5], v[20:21], v[4:5]
	v_cndmask_b32_e32 v31, v65, v31, vcc
	v_cmp_le_f32_e32 vcc, 0, v72
	v_pk_mul_f32 v[6:7], v[26:27], v[6:7]
	v_cvt_pk_bf16_f32 v4, v4, v5
	v_cndmask_b32_e32 v30, v64, v30, vcc
	v_cmp_le_f32_e32 vcc, 0, v75
	v_pk_mul_f32 v[30:31], v[16:17], v[30:31]
	v_cvt_pk_bf16_f32 v5, v6, v7
	v_cndmask_b32_e32 v59, v67, v59, vcc
	v_cmp_le_f32_e32 vcc, 0, v74
	v_pk_mul_f32 v[20:21], v[28:29], v[30:31]
	s_nop 0
	v_cndmask_b32_e32 v58, v66, v58, vcc
	v_pk_mul_f32 v[26:27], v[12:13], v[58:59]
	v_cvt_pk_bf16_f32 v6, v20, v21
	v_pk_mul_f32 v[10:11], v[10:11], v[26:27]
	v_sub_f32_e32 v20, v37, v55
	v_cvt_pk_bf16_f32 v7, v10, v11
	ds_write_b128 v2, v[4:7] offset:11584
	v_mov_b64_e32 v[4:5], v[246:247]
	v_mov_b64_e32 v[6:7], v[248:249]
	v_sub_f32_e32 v21, v39, v54
	v_sub_f32_e32 v10, v1, v57
	v_sub_f32_e32 v11, v35, v56
	v_sub_f32_e32 v24, v36, v53
	v_sub_f32_e32 v25, v38, v52
	v_sub_f32_e32 v26, v40, v51
	v_sub_f32_e32 v27, v41, v50
	v_mul_f32_e32 v28, 0x3fb8aa3b, v20
	v_mul_f32_e32 v29, 0x3fb8aa3b, v21
	v_mul_f32_e32 v10, 0x3fb8aa3b, v10
	v_mul_f32_e32 v11, 0x3fb8aa3b, v11
	v_mul_f32_e32 v30, 0x3fb8aa3b, v24
	v_mul_f32_e32 v31, 0x3fb8aa3b, v25
	v_mul_f32_e32 v50, 0x3fb8aa3b, v26
	v_mul_f32_e32 v51, 0x3fb8aa3b, v27
	v_exp_f32_e32 v24, v28
	v_exp_f32_e32 v25, v29
	v_exp_f32_e32 v20, v10
	v_exp_f32_e32 v21, v11
	v_exp_f32_e32 v10, v50
	v_exp_f32_e32 v11, v51
	v_exp_f32_e32 v26, v30
	v_exp_f32_e32 v27, v31
	s_waitcnt vmcnt(0) lgkmcnt(0)
; #define LAS __attribute__((address_space(3)))
; __device__ __forceinline__ u32x4 pack8(const float (&v)[8]) { u32x4 w; w.x = pk2(v[0], v[1]); w.y = pk2(v[2], v[3]); w.z = pk2(v[4], v[5]); w.w = pk2(v[6], v[7]); return w; }
; __device__ __forceinline__ void ld8bf(const bf16_t* p, float (&o)[8]) { unpack8(*(const u32x4*)p, o); }
; __device__ __forceinline__ void w_hg_m1(const Args& a, int l, unsigned char* ws, const bf16_t* proj, LAS unsigned char* wl, int b, int ck_, int h, int lane) {
;     ...
; #pragma unroll
;         for (int tb = 0; tb < 4; ++tb) { float fp[8]; ld8bf(fsrc + (size_t)(16 * tb + lo) * NIN, fp);
;             float kb[8];
; #pragma unroll
;             for (int j = 0; j < 8; ++j) { float lf, key; hg_lf_key(fp[j], lbv[j], lf, key); kb[j] = key * __expf(r63[j] - bb[tb][j]); }
;             *(LAS u32x4*)(kT + (16 * tb + lo) * LD + 32 * kk + 8 * fq) = pack8(kb); }
;         if (lo == 0) { float* dp = (float*)(ws + WS_HGDEC) + (size_t)((b * NCH + ck_) * 4 + h) * 64 + 32 * kk + 8 * fq;
; #pragma unroll
;             for (int j = 0; j < 8; ++j) dp[j] = __expf(r63[j]); }
	v_lshlrev_b32_e32 v58, 16, v4
	v_and_b32_e32 v59, 0xffff0000, v4
	v_lshlrev_b32_e32 v60, 16, v5
	v_and_b32_e32 v61, 0xffff0000, v5
	v_mul_f32_e64 v4, |v58|, s26
	v_mul_f32_e64 v5, |v59|, s26
	v_exp_f32_e32 v4, v4
	v_exp_f32_e32 v5, v5
	v_lshlrev_b32_e32 v62, 16, v6
	v_and_b32_e32 v63, 0xffff0000, v6
	v_lshlrev_b32_e32 v64, 16, v7
	v_and_b32_e32 v65, 0xffff0000, v7
	v_mul_f32_e64 v6, |v60|, s26
	v_mul_f32_e64 v7, |v61|, s26
	v_exp_f32_e32 v6, v6
	v_exp_f32_e32 v7, v7
	v_mul_f32_e64 v28, |v62|, s26
	v_mul_f32_e64 v29, |v63|, s26
	v_exp_f32_e32 v28, v28
	v_exp_f32_e32 v29, v29
	v_add_f32_e32 v50, 1.0, v4
	v_add_f32_e32 v51, 1.0, v5
	v_mul_f32_e64 v30, |v64|, s26
	v_mul_f32_e64 v31, |v65|, s26
	v_rcp_f32_e32 v50, v50
	v_rcp_f32_e32 v51, v51
	v_exp_f32_e32 v30, v30
	v_exp_f32_e32 v31, v31
	v_add_f32_e32 v52, 1.0, v6
	v_add_f32_e32 v53, 1.0, v7
	v_rcp_f32_e32 v52, v52
	v_rcp_f32_e32 v53, v53
	v_add_f32_e32 v54, 1.0, v28
	v_add_f32_e32 v55, 1.0, v29
	v_rcp_f32_e32 v54, v54
	v_rcp_f32_e32 v55, v55
	v_pk_mul_f32 v[4:5], v[4:5], v[50:51]
	v_cmp_le_f32_e32 vcc, 0, v59
	v_add_f32_e32 v56, 1.0, v30
	v_add_f32_e32 v57, 1.0, v31
	v_cndmask_b32_e32 v5, v51, v5, vcc
	v_cmp_le_f32_e32 vcc, 0, v58
	v_rcp_f32_e32 v56, v56
	v_rcp_f32_e32 v57, v57
	v_pk_mul_f32 v[6:7], v[6:7], v[52:53]
	v_cndmask_b32_e32 v4, v50, v4, vcc
	v_cmp_le_f32_e32 vcc, 0, v61
	v_pk_mul_f32 v[28:29], v[28:29], v[54:55]
	v_pk_mul_f32 v[30:31], v[30:31], v[56:57]
	v_cndmask_b32_e32 v7, v53, v7, vcc
	v_cmp_le_f32_e32 vcc, 0, v60
	v_pk_mul_f32 v[4:5], v[14:15], v[4:5]
	s_nop 0
	v_cndmask_b32_e32 v6, v52, v6, vcc
	v_cmp_le_f32_e32 vcc, 0, v63
	v_pk_mul_f32 v[6:7], v[18:19], v[6:7]
	v_pk_mul_f32 v[4:5], v[20:21], v[4:5]
	v_cndmask_b32_e32 v29, v55, v29, vcc
	v_cmp_le_f32_e32 vcc, 0, v62
	v_pk_mul_f32 v[6:7], v[24:25], v[6:7]
	v_cvt_pk_bf16_f32 v4, v4, v5
	v_cndmask_b32_e32 v28, v54, v28, vcc
	v_cmp_le_f32_e32 vcc, 0, v65
	v_pk_mul_f32 v[28:29], v[16:17], v[28:29]
	v_cvt_pk_bf16_f32 v5, v6, v7
	v_cndmask_b32_e32 v31, v57, v31, vcc
	v_cmp_le_f32_e32 vcc, 0, v64
	v_pk_mul_f32 v[20:21], v[26:27], v[28:29]
	s_nop 0
	v_cndmask_b32_e32 v30, v56, v30, vcc
	v_pk_mul_f32 v[24:25], v[12:13], v[30:31]
	v_cvt_pk_bf16_f32 v6, v20, v21
	v_pk_mul_f32 v[10:11], v[10:11], v[24:25]
	v_sub_f32_e32 v20, v37, v47
	v_cvt_pk_bf16_f32 v7, v10, v11
	ds_write_b128 v2, v[4:7] offset:13888
	v_mov_b64_e32 v[4:5], v[250:251]
	v_mov_b64_e32 v[6:7], v[252:253]
	v_sub_f32_e32 v10, v1, v49
	v_sub_f32_e32 v11, v35, v48
	v_sub_f32_e32 v21, v39, v46
	v_sub_f32_e32 v22, v36, v45
	v_sub_f32_e32 v23, v38, v44
	v_sub_f32_e32 v24, v40, v43
	v_sub_f32_e32 v25, v41, v42
	v_mul_f32_e32 v26, 0x3fb8aa3b, v20
	v_mul_f32_e32 v27, 0x3fb8aa3b, v21
	v_mul_f32_e32 v10, 0x3fb8aa3b, v10
	v_mul_f32_e32 v11, 0x3fb8aa3b, v11
	v_mul_f32_e32 v28, 0x3fb8aa3b, v22
	v_mul_f32_e32 v29, 0x3fb8aa3b, v23
	v_mul_f32_e32 v30, 0x3fb8aa3b, v24
	v_mul_f32_e32 v31, 0x3fb8aa3b, v25
	v_exp_f32_e32 v22, v26
	v_exp_f32_e32 v23, v27
	v_exp_f32_e32 v20, v10
	v_exp_f32_e32 v21, v11
	v_exp_f32_e32 v10, v30
	v_exp_f32_e32 v11, v31
	v_exp_f32_e32 v24, v28
	v_exp_f32_e32 v25, v29
	s_waitcnt vmcnt(0) lgkmcnt(0)
	v_lshlrev_b32_e32 v48, 16, v4
	v_and_b32_e32 v49, 0xffff0000, v4
	v_lshlrev_b32_e32 v50, 16, v5
	v_and_b32_e32 v51, 0xffff0000, v5
	v_mul_f32_e64 v4, |v48|, s26
	v_mul_f32_e64 v5, |v49|, s26
	v_exp_f32_e32 v4, v4
	v_exp_f32_e32 v5, v5
	v_lshlrev_b32_e32 v52, 16, v6
	v_and_b32_e32 v53, 0xffff0000, v6
	v_lshlrev_b32_e32 v54, 16, v7
	v_and_b32_e32 v55, 0xffff0000, v7
	v_mul_f32_e64 v6, |v50|, s26
	v_mul_f32_e64 v7, |v51|, s26
	v_exp_f32_e32 v6, v6
	v_exp_f32_e32 v7, v7
	v_mul_f32_e64 v26, |v52|, s26
	v_mul_f32_e64 v27, |v53|, s26
	v_exp_f32_e32 v26, v26
	v_exp_f32_e32 v27, v27
	v_add_f32_e32 v30, 1.0, v4
	v_add_f32_e32 v31, 1.0, v5
	v_mul_f32_e64 v28, |v54|, s26
	v_mul_f32_e64 v29, |v55|, s26
	v_rcp_f32_e32 v30, v30
	v_rcp_f32_e32 v31, v31
	v_exp_f32_e32 v28, v28
	v_exp_f32_e32 v29, v29
	v_add_f32_e32 v42, 1.0, v6
	v_add_f32_e32 v43, 1.0, v7
	v_rcp_f32_e32 v42, v42
	v_rcp_f32_e32 v43, v43
	v_add_f32_e32 v44, 1.0, v26
	v_add_f32_e32 v45, 1.0, v27
	v_rcp_f32_e32 v44, v44
	v_rcp_f32_e32 v45, v45
	v_pk_mul_f32 v[4:5], v[4:5], v[30:31]
	v_cmp_le_f32_e32 vcc, 0, v49
	v_add_f32_e32 v46, 1.0, v28
	v_add_f32_e32 v47, 1.0, v29
	v_cndmask_b32_e32 v5, v31, v5, vcc
	v_cmp_le_f32_e32 vcc, 0, v48
	v_rcp_f32_e32 v46, v46
	v_rcp_f32_e32 v47, v47
	v_pk_mul_f32 v[6:7], v[6:7], v[42:43]
	v_cndmask_b32_e32 v4, v30, v4, vcc
	v_cmp_le_f32_e32 vcc, 0, v51
	v_pk_mul_f32 v[26:27], v[26:27], v[44:45]
	v_pk_mul_f32 v[28:29], v[28:29], v[46:47]
	v_cndmask_b32_e32 v7, v43, v7, vcc
	v_cmp_le_f32_e32 vcc, 0, v50
	v_pk_mul_f32 v[4:5], v[14:15], v[4:5]
	s_nop 0
	v_cndmask_b32_e32 v6, v42, v6, vcc
	v_cmp_le_f32_e32 vcc, 0, v53
	v_pk_mul_f32 v[6:7], v[18:19], v[6:7]
	v_pk_mul_f32 v[4:5], v[20:21], v[4:5]
	v_cndmask_b32_e32 v27, v45, v27, vcc
	v_cmp_le_f32_e32 vcc, 0, v52
	v_pk_mul_f32 v[6:7], v[22:23], v[6:7]
	v_cvt_pk_bf16_f32 v4, v4, v5
	v_cndmask_b32_e32 v26, v44, v26, vcc
	v_cmp_le_f32_e32 vcc, 0, v55
	v_pk_mul_f32 v[14:15], v[16:17], v[26:27]
	v_cvt_pk_bf16_f32 v5, v6, v7
	v_cndmask_b32_e32 v17, v47, v29, vcc
	v_cmp_le_f32_e32 vcc, 0, v54
	v_pk_mul_f32 v[14:15], v[24:25], v[14:15]
	s_nop 0
	v_cndmask_b32_e32 v16, v46, v28, vcc
	v_pk_mul_f32 v[12:13], v[12:13], v[16:17]
	v_cvt_pk_bf16_f32 v6, v14, v15
	v_pk_mul_f32 v[10:11], v[10:11], v[12:13]
	s_nop 0
	v_cvt_pk_bf16_f32 v7, v10, v11
	ds_write_b128 v2, v[4:7] offset:16192
	s_and_saveexec_b64 s[34:35], s[38:39]
	s_cbranch_execz .LBB0_529
	v_mul_f32_e32 v1, 0x3fb8aa3b, v1
	v_exp_f32_e32 v4, v1
	v_mul_f32_e32 v1, 0x3fb8aa3b, v35
	v_exp_f32_e32 v5, v1
	v_mul_f32_e32 v1, 0x3fb8aa3b, v37
	v_exp_f32_e32 v6, v1
	v_mul_f32_e32 v1, 0x3fb8aa3b, v39
	v_exp_f32_e32 v7, v1
	v_mul_f32_e32 v1, 0x3fb8aa3b, v36
	global_store_dwordx4 v[8:9], v[4:7], off offset:128
	s_nop 1
	v_exp_f32_e32 v4, v1
	v_mul_f32_e32 v1, 0x3fb8aa3b, v38
	v_exp_f32_e32 v5, v1
	v_mul_f32_e32 v1, 0x3fb8aa3b, v40
	v_exp_f32_e32 v6, v1
	v_mul_f32_e32 v1, 0x3fb8aa3b, v41
	v_exp_f32_e32 v7, v1
	global_store_dwordx4 v[8:9], v[4:7], off offset:144
	s_branch .LBB0_529
